# nt also on last-reader z loads (pooling rows, SSM pass-2 fragments)
# speedup vs baseline: 1.0035x; 1.0035x over previous
; #define LAS __attribute__((address_space(3)))
; __device__ __forceinline__ unsigned cvt_pk_bf16(float lo, float hi) { const f32x2 v = {lo, hi}; return __builtin_bit_cast(unsigned, __builtin_convertvector(v, bfx2_t)); }
; __device__ __forceinline__ float bflo(unsigned w) { return __uint_as_float(w << 16); }
; template <int PASS> __device__ void ssm_pass(const Params& P, int l, LAS unsigned char* lds) {
;     ...
;             u32x2 unext = ucur; if (mt < 63) unext = *(const u32x2*)(zrow + (size_t)(mt + 1) * 16 * DM);
;             const bf16x4 af = __builtin_bit_cast(bf16x4, ucur);
;             f32x4 d[8];
; #pragma unroll
;             for (int t = 0; t < 8; ++t) d[t] = __builtin_amdgcn_mfma_f32_16x16x16bf16_1k(af, bf[t], (f32x4){0.f, 0.f, 0.f, 0.f}, 0, 0, 0);
; #pragma unroll
;             for (int tq = 0; tq < 4; ++tq)
; #pragma unroll
;                 for (int j = 0; j < 4; ++j) *(LAS f32x2*)(BU + (4 * fq + j) * 528 + (16 * tq + fr) * 8) = (f32x2){d[tq][j], d[tq + 4][j]};
;             asm volatile("s_waitcnt lgkmcnt(0)" ::: "memory");
; #pragma unroll
;             for (int j = 0; j < 16; ++j) {
;                 const f32x2 bu = *(const LAS f32x2*)(BU + j * 528 + lane * 8);
;                 sv = __builtin_elementwise_fma(ayn, __builtin_shufflevector(sv, sv, 1, 0), __builtin_elementwise_fma(axx, sv, bu));
;                 if (PASS == 2) *(LAS unsigned*)(SI + j * 272 + lane * 4) = cvt_pk_bf16(sv.x, sv.y);
;             }
;             if (PASS == 2) {
;                 asm volatile("s_waitcnt lgkmcnt(0)" ::: "memory");
;                 f32x4 acc = (f32x4){0.f, 0.f, 0.f, 0.f};
; #pragma unroll
;                 for (int kt = 0; kt < 4; ++kt) { const bf16x8 sv = *(const LAS bf16x8*)(SI + fr * 272 + (32 * kt + 8 * fq) * 2);
;                     acc = __builtin_amdgcn_mfma_f32_16x16x32_bf16(cf[kt], sv, acc, 0, 0, 0); }
;                 const size_t tok = tok0 + 16 * mt + fr;
;                 float o[4];
;                 const float uf[4] = {bflo(ucur.x), bfhi(ucur.x), bflo(ucur.y), bfhi(ucur.y)};
; #pragma unroll
;                 for (int j = 0; j < 4; ++j) { const float y = acc[j] + dd[j] * uf[j]; o[j] = y * fsigmoid(1.5957691216057308f * (y + 0.044715f * y * y * y)); }
;                 u32x2 w; w.x = cvt_pk_bf16(o[0], o[1]); w.y = cvt_pk_bf16(o[2], o[3]);
;                 *(u32x2*)(ypre + tok * 512 + g * 16 + 4 * fq) = w;
;             }
.Lp2_loop:
	s_waitcnt vmcnt(9)
	ds_write_b64 v146, v[62:63]
	ds_read_b128 v[192:195], v69 offset:8448
	ds_read_b128 v[204:207], v69 offset:8512
	ds_read_b128 v[212:215], v69 offset:8576
	ds_read_b128 v[216:219], v69 offset:8640
	ds_read_b128 v[156:159], v196
	ds_read_b128 v[200:203], v197
	global_load_dwordx2 v[144:145], v[60:61], off nt
	v_lshl_add_u64 v[60:61], v[60:61], 0, s[18:19]
	v_fma_f32 v70, v56, v54, v88
	v_fma_f32 v71, v56, v55, v104
	v_lshlrev_b32_e32 v76, 16, v148
	v_fma_f32 v72, v36, v55, v70
	v_fma_f32 v73, v37, v54, v71
	v_cvt_pk_bf16_f32 v74, v72, v73
	v_and_b32_e32 v77, 0xffff0000, v148
	v_fma_f32 v70, v56, v72, v89
	v_fma_f32 v71, v56, v73, v105
	v_lshlrev_b32_e32 v78, 16, v149
	v_fma_f32 v54, v36, v73, v70
	v_fma_f32 v55, v37, v72, v71
	v_cvt_pk_bf16_f32 v75, v54, v55
	v_and_b32_e32 v79, 0xffff0000, v149
	ds_write2_b32 v242, v74, v75 offset0:0 offset1:68
	s_waitcnt lgkmcnt(3)
	v_mfma_f32_16x16x32_bf16 v[220:223], v[0:3], v[192:195], 0
	v_mfma_f32_16x16x32_bf16 v[220:223], v[4:7], v[204:207], v[220:223]
	v_mfma_f32_16x16x32_bf16 v[220:223], v[8:11], v[212:215], v[220:223]
	v_mfma_f32_16x16x32_bf16 v[220:223], v[12:15], v[216:219], v[220:223]
	v_fma_f32 v70, v56, v54, v90
	v_fma_f32 v71, v56, v55, v106
	v_fma_f32 v72, v36, v55, v70
	v_fma_f32 v73, v37, v54, v71
	v_cvt_pk_bf16_f32 v74, v72, v73
	v_fma_f32 v70, v56, v72, v91
	v_fma_f32 v71, v56, v73, v107
	v_fma_f32 v54, v36, v73, v70
	v_fma_f32 v55, v37, v72, v71
	v_cvt_pk_bf16_f32 v75, v54, v55
	ds_write2_b32 v242, v74, v75 offset0:136 offset1:204
	s_waitcnt lgkmcnt(2)
	v_mfma_f32_32x32x16_bf16 v[120:135], v[156:159], v[38:41], 0
	v_mfma_f32_32x32x16_bf16 v[226:241], v[156:159], v[46:49], 0
	v_fma_f32 v70, v56, v54, v92
	v_fma_f32 v71, v56, v55, v108
	v_fma_f32 v80, v16, v76, v220
	v_fma_f32 v81, v17, v77, v221
	v_fma_f32 v72, v36, v55, v70
	v_fma_f32 v73, v37, v54, v71
	v_cvt_pk_bf16_f32 v74, v72, v73
	v_fma_f32 v82, v18, v78, v222
	v_fma_f32 v83, v19, v79, v223
	v_fma_f32 v70, v56, v72, v93
	v_fma_f32 v71, v56, v73, v109
	v_mul_f32_e32 v84, 0x3d372713, v80
	v_mul_f32_e32 v85, 0x3d372713, v81
	v_fma_f32 v54, v36, v73, v70
	v_fma_f32 v55, v37, v72, v71
	v_cvt_pk_bf16_f32 v75, v54, v55
	v_mul_f32_e32 v86, 0x3d372713, v82
	v_mul_f32_e32 v87, 0x3d372713, v83
	ds_write2_b32 v243, v74, v75 offset0:0 offset1:68
	v_mfma_f32_32x32x16_bf16 v[120:135], v[200:203], v[42:45], v[120:135]
	v_mfma_f32_32x32x16_bf16 v[226:241], v[200:203], v[50:53], v[226:241]
	v_fma_f32 v70, v56, v54, v94
	v_fma_f32 v71, v56, v55, v110
	v_mul_f32_e32 v84, v80, v84
	v_mul_f32_e32 v85, v81, v85
	v_fma_f32 v72, v36, v55, v70
	v_fma_f32 v73, v37, v54, v71
	v_cvt_pk_bf16_f32 v74, v72, v73
	v_mul_f32_e32 v86, v82, v86
	v_mul_f32_e32 v87, v83, v87
	v_fma_f32 v70, v56, v72, v95
	v_fma_f32 v71, v56, v73, v111
	v_fma_f32 v84, v80, v84, v80
	v_fma_f32 v85, v81, v85, v81
	v_fma_f32 v54, v36, v73, v70
	v_fma_f32 v55, v37, v72, v71
	v_cvt_pk_bf16_f32 v75, v54, v55
	v_fma_f32 v86, v82, v86, v82
	v_fma_f32 v87, v83, v87, v83
	ds_write2_b32 v243, v74, v75 offset0:136 offset1:204
	v_fma_f32 v70, v56, v54, v96
	v_fma_f32 v71, v56, v55, v112
	v_mul_f32_e32 v84, 0x3fcc422a, v84
	v_mul_f32_e32 v85, 0x3fcc422a, v85
	v_fma_f32 v72, v36, v55, v70
	v_fma_f32 v73, v37, v54, v71
	v_cvt_pk_bf16_f32 v74, v72, v73
	v_mul_f32_e32 v86, 0x3fcc422a, v86
	v_mul_f32_e32 v87, 0x3fcc422a, v87
	v_fma_f32 v70, v56, v72, v97
	v_fma_f32 v71, v56, v73, v113
	v_mul_f32_e32 v84, 0xbfb8aa3b, v84
	v_mul_f32_e32 v85, 0xbfb8aa3b, v85
	v_fma_f32 v54, v36, v73, v70
	v_fma_f32 v55, v37, v72, v71
	v_cvt_pk_bf16_f32 v75, v54, v55
	v_mul_f32_e32 v86, 0xbfb8aa3b, v86
	ds_write2_b32 v244, v74, v75 offset0:0 offset1:68
	v_fma_f32 v70, v56, v54, v98
	v_fma_f32 v71, v56, v55, v114
	v_mul_f32_e32 v87, 0xbfb8aa3b, v87
	v_exp_f32_e32 v84, v84
	v_fma_f32 v72, v36, v55, v70
	v_fma_f32 v73, v37, v54, v71
	v_cvt_pk_bf16_f32 v74, v72, v73
	v_exp_f32_e32 v85, v85
	v_exp_f32_e32 v86, v86
	v_fma_f32 v70, v56, v72, v99
	v_fma_f32 v71, v56, v73, v115
	v_exp_f32_e32 v87, v87
	v_add_f32_e32 v84, 1.0, v84
	v_fma_f32 v54, v36, v73, v70
	v_fma_f32 v55, v37, v72, v71
	v_cvt_pk_bf16_f32 v75, v54, v55
	v_add_f32_e32 v85, 1.0, v85
	ds_write2_b32 v244, v74, v75 offset0:136 offset1:204
	v_fma_f32 v70, v56, v54, v100
	v_fma_f32 v71, v56, v55, v116
	v_add_f32_e32 v86, 1.0, v86
	v_add_f32_e32 v87, 1.0, v87
	v_fma_f32 v72, v36, v55, v70
	v_fma_f32 v73, v37, v54, v71
	v_cvt_pk_bf16_f32 v74, v72, v73
	v_rcp_f32_e32 v84, v84
	v_rcp_f32_e32 v85, v85
	v_fma_f32 v70, v56, v72, v101
	v_fma_f32 v71, v56, v73, v117
	v_rcp_f32_e32 v86, v86
	v_rcp_f32_e32 v87, v87
	v_fma_f32 v54, v36, v73, v70
	v_fma_f32 v55, v37, v72, v71
	v_cvt_pk_bf16_f32 v75, v54, v55
	s_nop 0
	ds_write2_b32 v245, v74, v75 offset0:0 offset1:68
	v_fma_f32 v70, v56, v54, v102
	v_fma_f32 v71, v56, v55, v118
	v_mul_f32_e32 v84, v80, v84
	v_mul_f32_e32 v85, v81, v85
	v_fma_f32 v72, v36, v55, v70
	v_fma_f32 v73, v37, v54, v71
	v_cvt_pk_bf16_f32 v74, v72, v73
	v_mul_f32_e32 v86, v82, v86
	v_mul_f32_e32 v87, v83, v87
	v_fma_f32 v70, v56, v72, v103
	v_fma_f32 v71, v56, v73, v119
	v_cvt_pk_bf16_f32 v84, v84, v85
	v_fma_f32 v54, v36, v73, v70
	v_fma_f32 v55, v37, v72, v71
	v_cvt_pk_bf16_f32 v75, v54, v55
	v_cvt_pk_bf16_f32 v85, v86, v87
	ds_write2_b32 v245, v74, v75 offset0:136 offset1:204
	s_cmp_eq_u32 s12, 0
	s_cbranch_scc1 .Lp2_skip
	global_store_dwordx2 v[246:247], v[84:85], off
	s_mov_b64 s[18:19], 0x4000
	v_lshl_add_u64 v[246:247], v[246:247], 0, s[18:19]
	s_mov_b64 s[18:19], 0x8000
	s_branch .Lp2_join

; #define LAS __attribute__((address_space(3)))
; __device__ __forceinline__ unsigned cvt_pk_bf16(float lo, float hi) { const f32x2 v = {lo, hi}; return __builtin_bit_cast(unsigned, __builtin_convertvector(v, bfx2_t)); }
; __device__ __forceinline__ float bflo(unsigned w) { return __uint_as_float(w << 16); }
; template <int PASS> __device__ void ssm_pass(const Params& P, int l, LAS unsigned char* lds) {
;     ...
;             u32x2 unext = ucur; if (mt < 63) unext = *(const u32x2*)(zrow + (size_t)(mt + 1) * 16 * DM);
;             const bf16x4 af = __builtin_bit_cast(bf16x4, ucur);
;             f32x4 d[8];
; #pragma unroll
;             for (int t = 0; t < 8; ++t) d[t] = __builtin_amdgcn_mfma_f32_16x16x16bf16_1k(af, bf[t], (f32x4){0.f, 0.f, 0.f, 0.f}, 0, 0, 0);
; #pragma unroll
;             for (int tq = 0; tq < 4; ++tq)
; #pragma unroll
;                 for (int j = 0; j < 4; ++j) *(LAS f32x2*)(BU + (4 * fq + j) * 528 + (16 * tq + fr) * 8) = (f32x2){d[tq][j], d[tq + 4][j]};
;             asm volatile("s_waitcnt lgkmcnt(0)" ::: "memory");
; #pragma unroll
;             for (int j = 0; j < 16; ++j) {
;                 const f32x2 bu = *(const LAS f32x2*)(BU + j * 528 + lane * 8);
;                 sv = __builtin_elementwise_fma(ayn, __builtin_shufflevector(sv, sv, 1, 0), __builtin_elementwise_fma(axx, sv, bu));
;                 if (PASS == 2) *(LAS unsigned*)(SI + j * 272 + lane * 4) = cvt_pk_bf16(sv.x, sv.y);
;             }
;             if (PASS == 2) {
;                 asm volatile("s_waitcnt lgkmcnt(0)" ::: "memory");
;                 f32x4 acc = (f32x4){0.f, 0.f, 0.f, 0.f};
; #pragma unroll
;                 for (int kt = 0; kt < 4; ++kt) { const bf16x8 sv = *(const LAS bf16x8*)(SI + fr * 272 + (32 * kt + 8 * fq) * 2);
;                     acc = __builtin_amdgcn_mfma_f32_16x16x32_bf16(cf[kt], sv, acc, 0, 0, 0); }
;                 const size_t tok = tok0 + 16 * mt + fr;
;                 float o[4];
;                 const float uf[4] = {bflo(ucur.x), bfhi(ucur.x), bflo(ucur.y), bfhi(ucur.y)};
; #pragma unroll
;                 for (int j = 0; j < 4; ++j) { const float y = acc[j] + dd[j] * uf[j]; o[j] = y * fsigmoid(1.5957691216057308f * (y + 0.044715f * y * y * y)); }
;                 u32x2 w; w.x = cvt_pk_bf16(o[0], o[1]); w.y = cvt_pk_bf16(o[2], o[3]);
;                 *(u32x2*)(ypre + tok * 512 + g * 16 + 4 * fq) = w;
;             }
.Lp2_join:
	s_waitcnt vmcnt(9)
	ds_write_b64 v146, v[136:137]
	ds_read_b128 v[192:195], v69 offset:8448
	ds_read_b128 v[204:207], v69 offset:8512
	ds_read_b128 v[212:215], v69 offset:8576
	ds_read_b128 v[216:219], v69 offset:8640
	ds_read_b128 v[156:159], v196
	ds_read_b128 v[200:203], v197
	global_load_dwordx2 v[148:149], v[60:61], off nt
	v_lshl_add_u64 v[60:61], v[60:61], 0, s[18:19]
	v_fma_f32 v70, v56, v54, v120
	v_fma_f32 v71, v56, v55, v226
	v_lshlrev_b32_e32 v76, 16, v64
	v_fma_f32 v72, v36, v55, v70
	v_fma_f32 v73, v37, v54, v71
	v_cvt_pk_bf16_f32 v74, v72, v73
	v_and_b32_e32 v77, 0xffff0000, v64
	v_fma_f32 v70, v56, v72, v121
	v_fma_f32 v71, v56, v73, v227
	v_lshlrev_b32_e32 v78, 16, v65
	v_fma_f32 v54, v36, v73, v70
	v_fma_f32 v55, v37, v72, v71
	v_cvt_pk_bf16_f32 v75, v54, v55
	v_and_b32_e32 v79, 0xffff0000, v65
	ds_write2_b32 v242, v74, v75 offset0:0 offset1:68
	s_waitcnt lgkmcnt(3)
	v_mfma_f32_16x16x32_bf16 v[220:223], v[0:3], v[192:195], 0
	v_mfma_f32_16x16x32_bf16 v[220:223], v[4:7], v[204:207], v[220:223]
	v_mfma_f32_16x16x32_bf16 v[220:223], v[8:11], v[212:215], v[220:223]
	v_mfma_f32_16x16x32_bf16 v[220:223], v[12:15], v[216:219], v[220:223]
	v_fma_f32 v70, v56, v54, v122
	v_fma_f32 v71, v56, v55, v228
	v_fma_f32 v72, v36, v55, v70
	v_fma_f32 v73, v37, v54, v71
	v_cvt_pk_bf16_f32 v74, v72, v73
	v_fma_f32 v70, v56, v72, v123
	v_fma_f32 v71, v56, v73, v229
	v_fma_f32 v54, v36, v73, v70
	v_fma_f32 v55, v37, v72, v71
	v_cvt_pk_bf16_f32 v75, v54, v55
	ds_write2_b32 v242, v74, v75 offset0:136 offset1:204
	s_waitcnt lgkmcnt(2)
	v_mfma_f32_32x32x16_bf16 v[88:103], v[156:159], v[38:41], 0
	v_mfma_f32_32x32x16_bf16 v[104:119], v[156:159], v[46:49], 0
	v_fma_f32 v70, v56, v54, v124
	v_fma_f32 v71, v56, v55, v230
	v_fma_f32 v80, v16, v76, v220
	v_fma_f32 v81, v17, v77, v221
	v_fma_f32 v72, v36, v55, v70
	v_fma_f32 v73, v37, v54, v71
	v_cvt_pk_bf16_f32 v74, v72, v73
	v_fma_f32 v82, v18, v78, v222
	v_fma_f32 v83, v19, v79, v223
	v_fma_f32 v70, v56, v72, v125
	v_fma_f32 v71, v56, v73, v231
	v_mul_f32_e32 v84, 0x3d372713, v80
	v_mul_f32_e32 v85, 0x3d372713, v81
	v_fma_f32 v54, v36, v73, v70
	v_fma_f32 v55, v37, v72, v71
	v_cvt_pk_bf16_f32 v75, v54, v55
	v_mul_f32_e32 v86, 0x3d372713, v82
	v_mul_f32_e32 v87, 0x3d372713, v83
	ds_write2_b32 v243, v74, v75 offset0:0 offset1:68
	v_mfma_f32_32x32x16_bf16 v[88:103], v[200:203], v[42:45], v[88:103]
	v_mfma_f32_32x32x16_bf16 v[104:119], v[200:203], v[50:53], v[104:119]
	v_fma_f32 v70, v56, v54, v126
	v_fma_f32 v71, v56, v55, v232
	v_mul_f32_e32 v84, v80, v84
	v_mul_f32_e32 v85, v81, v85
	v_fma_f32 v72, v36, v55, v70
	v_fma_f32 v73, v37, v54, v71
	v_cvt_pk_bf16_f32 v74, v72, v73
	v_mul_f32_e32 v86, v82, v86
	v_mul_f32_e32 v87, v83, v87
	v_fma_f32 v70, v56, v72, v127
	v_fma_f32 v71, v56, v73, v233
	v_fma_f32 v84, v80, v84, v80
	v_fma_f32 v85, v81, v85, v81
	v_fma_f32 v54, v36, v73, v70
	v_fma_f32 v55, v37, v72, v71
	v_cvt_pk_bf16_f32 v75, v54, v55
	v_fma_f32 v86, v82, v86, v82
	v_fma_f32 v87, v83, v87, v83
	ds_write2_b32 v243, v74, v75 offset0:136 offset1:204
	v_fma_f32 v70, v56, v54, v128
	v_fma_f32 v71, v56, v55, v234
	v_mul_f32_e32 v84, 0x3fcc422a, v84
	v_mul_f32_e32 v85, 0x3fcc422a, v85
	v_fma_f32 v72, v36, v55, v70
	v_fma_f32 v73, v37, v54, v71
	v_cvt_pk_bf16_f32 v74, v72, v73
	v_mul_f32_e32 v86, 0x3fcc422a, v86
	v_mul_f32_e32 v87, 0x3fcc422a, v87
	v_fma_f32 v70, v56, v72, v129
	v_fma_f32 v71, v56, v73, v235
	v_mul_f32_e32 v84, 0xbfb8aa3b, v84
	v_mul_f32_e32 v85, 0xbfb8aa3b, v85
	v_fma_f32 v54, v36, v73, v70
	v_fma_f32 v55, v37, v72, v71
	v_cvt_pk_bf16_f32 v75, v54, v55
	v_mul_f32_e32 v86, 0xbfb8aa3b, v86
	ds_write2_b32 v244, v74, v75 offset0:0 offset1:68
	v_fma_f32 v70, v56, v54, v130
	v_fma_f32 v71, v56, v55, v236
	v_mul_f32_e32 v87, 0xbfb8aa3b, v87
	v_exp_f32_e32 v84, v84
	v_fma_f32 v72, v36, v55, v70
	v_fma_f32 v73, v37, v54, v71
	v_cvt_pk_bf16_f32 v74, v72, v73
	v_exp_f32_e32 v85, v85
	v_exp_f32_e32 v86, v86
	v_fma_f32 v70, v56, v72, v131
	v_fma_f32 v71, v56, v73, v237
	v_exp_f32_e32 v87, v87
	v_add_f32_e32 v84, 1.0, v84
	v_fma_f32 v54, v36, v73, v70
	v_fma_f32 v55, v37, v72, v71
	v_cvt_pk_bf16_f32 v75, v54, v55
	v_add_f32_e32 v85, 1.0, v85
	ds_write2_b32 v244, v74, v75 offset0:136 offset1:204
	v_fma_f32 v70, v56, v54, v132
	v_fma_f32 v71, v56, v55, v238
	v_add_f32_e32 v86, 1.0, v86
	v_add_f32_e32 v87, 1.0, v87
	v_fma_f32 v72, v36, v55, v70
	v_fma_f32 v73, v37, v54, v71
	v_cvt_pk_bf16_f32 v74, v72, v73
	v_rcp_f32_e32 v84, v84
	v_rcp_f32_e32 v85, v85
	v_fma_f32 v70, v56, v72, v133
	v_fma_f32 v71, v56, v73, v239
	v_rcp_f32_e32 v86, v86
	v_rcp_f32_e32 v87, v87
	v_fma_f32 v54, v36, v73, v70
	v_fma_f32 v55, v37, v72, v71
	v_cvt_pk_bf16_f32 v75, v54, v55
	s_nop 0
	ds_write2_b32 v245, v74, v75 offset0:0 offset1:68
	v_fma_f32 v70, v56, v54, v134
	v_fma_f32 v71, v56, v55, v240
	v_mul_f32_e32 v84, v80, v84
	v_mul_f32_e32 v85, v81, v85
	v_fma_f32 v72, v36, v55, v70
	v_fma_f32 v73, v37, v54, v71
	v_cvt_pk_bf16_f32 v74, v72, v73
	v_mul_f32_e32 v86, v82, v86
	v_mul_f32_e32 v87, v83, v87
	v_fma_f32 v70, v56, v72, v135
	v_fma_f32 v71, v56, v73, v241
	v_cvt_pk_bf16_f32 v84, v84, v85
	v_fma_f32 v54, v36, v73, v70
	v_fma_f32 v55, v37, v72, v71
	v_cvt_pk_bf16_f32 v75, v54, v55
	v_cvt_pk_bf16_f32 v85, v86, v87
	ds_write2_b32 v245, v74, v75 offset0:136 offset1:204
	global_store_dwordx2 v[246:247], v[84:85], off
	s_mov_b64 s[18:19], 0x4000
	v_lshl_add_u64 v[246:247], v[246:247], 0, s[18:19]
	s_mov_b64 s[18:19], 0x8000
	s_waitcnt vmcnt(9)
; #define LAS __attribute__((address_space(3)))
; __device__ __forceinline__ unsigned cvt_pk_bf16(float lo, float hi) { const f32x2 v = {lo, hi}; return __builtin_bit_cast(unsigned, __builtin_convertvector(v, bfx2_t)); }
; __device__ __forceinline__ float bflo(unsigned w) { return __uint_as_float(w << 16); }
; template <int PASS> __device__ void ssm_pass(const Params& P, int l, LAS unsigned char* lds) {
;     ...
;             u32x2 unext = ucur; if (mt < 63) unext = *(const u32x2*)(zrow + (size_t)(mt + 1) * 16 * DM);
;             const bf16x4 af = __builtin_bit_cast(bf16x4, ucur);
;             f32x4 d[8];
; #pragma unroll
;             for (int t = 0; t < 8; ++t) d[t] = __builtin_amdgcn_mfma_f32_16x16x16bf16_1k(af, bf[t], (f32x4){0.f, 0.f, 0.f, 0.f}, 0, 0, 0);
; #pragma unroll
;             for (int tq = 0; tq < 4; ++tq)
; #pragma unroll
;                 for (int j = 0; j < 4; ++j) *(LAS f32x2*)(BU + (4 * fq + j) * 528 + (16 * tq + fr) * 8) = (f32x2){d[tq][j], d[tq + 4][j]};
;             asm volatile("s_waitcnt lgkmcnt(0)" ::: "memory");
; #pragma unroll
;             for (int j = 0; j < 16; ++j) {
;                 const f32x2 bu = *(const LAS f32x2*)(BU + j * 528 + lane * 8);
;                 sv = __builtin_elementwise_fma(ayn, __builtin_shufflevector(sv, sv, 1, 0), __builtin_elementwise_fma(axx, sv, bu));
;                 if (PASS == 2) *(LAS unsigned*)(SI + j * 272 + lane * 4) = cvt_pk_bf16(sv.x, sv.y);
;             }
;             if (PASS == 2) {
;                 asm volatile("s_waitcnt lgkmcnt(0)" ::: "memory");
;                 f32x4 acc = (f32x4){0.f, 0.f, 0.f, 0.f};
; #pragma unroll
;                 for (int kt = 0; kt < 4; ++kt) { const bf16x8 sv = *(const LAS bf16x8*)(SI + fr * 272 + (32 * kt + 8 * fq) * 2);
;                     acc = __builtin_amdgcn_mfma_f32_16x16x32_bf16(cf[kt], sv, acc, 0, 0, 0); }
;                 const size_t tok = tok0 + 16 * mt + fr;
;                 float o[4];
;                 const float uf[4] = {bflo(ucur.x), bfhi(ucur.x), bflo(ucur.y), bfhi(ucur.y)};
; #pragma unroll
;                 for (int j = 0; j < 4; ++j) { const float y = acc[j] + dd[j] * uf[j]; o[j] = y * fsigmoid(1.5957691216057308f * (y + 0.044715f * y * y * y)); }
;                 u32x2 w; w.x = cvt_pk_bf16(o[0], o[1]); w.y = cvt_pk_bf16(o[2], o[3]);
;                 *(u32x2*)(ypre + tok * 512 + g * 16 + 4 * fq) = w;
;             }
	ds_write_b64 v146, v[138:139]
	ds_read_b128 v[192:195], v69 offset:8448
	ds_read_b128 v[204:207], v69 offset:8512
	ds_read_b128 v[212:215], v69 offset:8576
	ds_read_b128 v[216:219], v69 offset:8640
	ds_read_b128 v[156:159], v196
	ds_read_b128 v[200:203], v197
	global_load_dwordx2 v[64:65], v[60:61], off nt
	v_lshl_add_u64 v[60:61], v[60:61], 0, s[18:19]
	v_fma_f32 v70, v56, v54, v88
	v_fma_f32 v71, v56, v55, v104
	v_lshlrev_b32_e32 v76, 16, v62
	v_fma_f32 v72, v36, v55, v70
	v_fma_f32 v73, v37, v54, v71
	v_cvt_pk_bf16_f32 v74, v72, v73
	v_and_b32_e32 v77, 0xffff0000, v62
	v_fma_f32 v70, v56, v72, v89
	v_fma_f32 v71, v56, v73, v105
	v_lshlrev_b32_e32 v78, 16, v63
	v_fma_f32 v54, v36, v73, v70
	v_fma_f32 v55, v37, v72, v71
	v_cvt_pk_bf16_f32 v75, v54, v55
	v_and_b32_e32 v79, 0xffff0000, v63
	ds_write2_b32 v242, v74, v75 offset0:0 offset1:68
	s_waitcnt lgkmcnt(3)
	v_mfma_f32_16x16x32_bf16 v[220:223], v[0:3], v[192:195], 0
	v_mfma_f32_16x16x32_bf16 v[220:223], v[4:7], v[204:207], v[220:223]
	v_mfma_f32_16x16x32_bf16 v[220:223], v[8:11], v[212:215], v[220:223]
	v_mfma_f32_16x16x32_bf16 v[220:223], v[12:15], v[216:219], v[220:223]
	v_fma_f32 v70, v56, v54, v90
	v_fma_f32 v71, v56, v55, v106
	v_fma_f32 v72, v36, v55, v70
	v_fma_f32 v73, v37, v54, v71
	v_cvt_pk_bf16_f32 v74, v72, v73
	v_fma_f32 v70, v56, v72, v91
	v_fma_f32 v71, v56, v73, v107
	v_fma_f32 v54, v36, v73, v70
	v_fma_f32 v55, v37, v72, v71
	v_cvt_pk_bf16_f32 v75, v54, v55
	ds_write2_b32 v242, v74, v75 offset0:136 offset1:204
	s_waitcnt lgkmcnt(2)
	v_mfma_f32_32x32x16_bf16 v[120:135], v[156:159], v[38:41], 0
	v_mfma_f32_32x32x16_bf16 v[226:241], v[156:159], v[46:49], 0
	v_fma_f32 v70, v56, v54, v92
	v_fma_f32 v71, v56, v55, v108
	v_fma_f32 v80, v16, v76, v220
	v_fma_f32 v81, v17, v77, v221
	v_fma_f32 v72, v36, v55, v70
	v_fma_f32 v73, v37, v54, v71
	v_cvt_pk_bf16_f32 v74, v72, v73
	v_fma_f32 v82, v18, v78, v222
	v_fma_f32 v83, v19, v79, v223
	v_fma_f32 v70, v56, v72, v93
	v_fma_f32 v71, v56, v73, v109
	v_mul_f32_e32 v84, 0x3d372713, v80
	v_mul_f32_e32 v85, 0x3d372713, v81
	v_fma_f32 v54, v36, v73, v70
	v_fma_f32 v55, v37, v72, v71
	v_cvt_pk_bf16_f32 v75, v54, v55
	v_mul_f32_e32 v86, 0x3d372713, v82
	v_mul_f32_e32 v87, 0x3d372713, v83
	ds_write2_b32 v243, v74, v75 offset0:0 offset1:68
	v_mfma_f32_32x32x16_bf16 v[120:135], v[200:203], v[42:45], v[120:135]
	v_mfma_f32_32x32x16_bf16 v[226:241], v[200:203], v[50:53], v[226:241]
	v_fma_f32 v70, v56, v54, v94
	v_fma_f32 v71, v56, v55, v110
	v_mul_f32_e32 v84, v80, v84
	v_mul_f32_e32 v85, v81, v85
	v_fma_f32 v72, v36, v55, v70
	v_fma_f32 v73, v37, v54, v71
	v_cvt_pk_bf16_f32 v74, v72, v73
	v_mul_f32_e32 v86, v82, v86
	v_mul_f32_e32 v87, v83, v87
	v_fma_f32 v70, v56, v72, v95
	v_fma_f32 v71, v56, v73, v111
	v_fma_f32 v84, v80, v84, v80
	v_fma_f32 v85, v81, v85, v81
	v_fma_f32 v54, v36, v73, v70
	v_fma_f32 v55, v37, v72, v71
	v_cvt_pk_bf16_f32 v75, v54, v55
	v_fma_f32 v86, v82, v86, v82
	v_fma_f32 v87, v83, v87, v83
	ds_write2_b32 v243, v74, v75 offset0:136 offset1:204
	v_fma_f32 v70, v56, v54, v96
	v_fma_f32 v71, v56, v55, v112
	v_mul_f32_e32 v84, 0x3fcc422a, v84
	v_mul_f32_e32 v85, 0x3fcc422a, v85
	v_fma_f32 v72, v36, v55, v70
	v_fma_f32 v73, v37, v54, v71
	v_cvt_pk_bf16_f32 v74, v72, v73
	v_mul_f32_e32 v86, 0x3fcc422a, v86
	v_mul_f32_e32 v87, 0x3fcc422a, v87
	v_fma_f32 v70, v56, v72, v97
	v_fma_f32 v71, v56, v73, v113
	v_mul_f32_e32 v84, 0xbfb8aa3b, v84
	v_mul_f32_e32 v85, 0xbfb8aa3b, v85
	v_fma_f32 v54, v36, v73, v70
	v_fma_f32 v55, v37, v72, v71
	v_cvt_pk_bf16_f32 v75, v54, v55
	v_mul_f32_e32 v86, 0xbfb8aa3b, v86
	ds_write2_b32 v244, v74, v75 offset0:0 offset1:68
	v_fma_f32 v70, v56, v54, v98
	v_fma_f32 v71, v56, v55, v114
	v_mul_f32_e32 v87, 0xbfb8aa3b, v87
	v_exp_f32_e32 v84, v84
	v_fma_f32 v72, v36, v55, v70
	v_fma_f32 v73, v37, v54, v71
	v_cvt_pk_bf16_f32 v74, v72, v73
	v_exp_f32_e32 v85, v85
	v_exp_f32_e32 v86, v86
	v_fma_f32 v70, v56, v72, v99
	v_fma_f32 v71, v56, v73, v115
	v_exp_f32_e32 v87, v87
	v_add_f32_e32 v84, 1.0, v84
	v_fma_f32 v54, v36, v73, v70
	v_fma_f32 v55, v37, v72, v71
	v_cvt_pk_bf16_f32 v75, v54, v55
	v_add_f32_e32 v85, 1.0, v85
	ds_write2_b32 v244, v74, v75 offset0:136 offset1:204
	v_fma_f32 v70, v56, v54, v100
	v_fma_f32 v71, v56, v55, v116
	v_add_f32_e32 v86, 1.0, v86
	v_add_f32_e32 v87, 1.0, v87
	v_fma_f32 v72, v36, v55, v70
	v_fma_f32 v73, v37, v54, v71
	v_cvt_pk_bf16_f32 v74, v72, v73
	v_rcp_f32_e32 v84, v84
	v_rcp_f32_e32 v85, v85
	v_fma_f32 v70, v56, v72, v101
	v_fma_f32 v71, v56, v73, v117
	v_rcp_f32_e32 v86, v86
	v_rcp_f32_e32 v87, v87
	v_fma_f32 v54, v36, v73, v70
	v_fma_f32 v55, v37, v72, v71
	v_cvt_pk_bf16_f32 v75, v54, v55
	s_nop 0
	ds_write2_b32 v245, v74, v75 offset0:0 offset1:68
	v_fma_f32 v70, v56, v54, v102
	v_fma_f32 v71, v56, v55, v118
	v_mul_f32_e32 v84, v80, v84
	v_mul_f32_e32 v85, v81, v85
	v_fma_f32 v72, v36, v55, v70
	v_fma_f32 v73, v37, v54, v71
	v_cvt_pk_bf16_f32 v74, v72, v73
	v_mul_f32_e32 v86, v82, v86
	v_mul_f32_e32 v87, v83, v87
	v_fma_f32 v70, v56, v72, v103
	v_fma_f32 v71, v56, v73, v119
	v_cvt_pk_bf16_f32 v84, v84, v85
	v_fma_f32 v54, v36, v73, v70
	v_fma_f32 v55, v37, v72, v71
	v_cvt_pk_bf16_f32 v75, v54, v55
	v_cvt_pk_bf16_f32 v85, v86, v87
	ds_write2_b32 v245, v74, v75 offset0:136 offset1:204
	global_store_dwordx2 v[246:247], v[84:85], off
	s_mov_b64 s[18:19], 0x4000
	v_lshl_add_u64 v[246:247], v[246:247], 0, s[18:19]
	s_mov_b64 s[18:19], 0x8000
	s_waitcnt vmcnt(9)
; #define LAS __attribute__((address_space(3)))
; __device__ __forceinline__ unsigned cvt_pk_bf16(float lo, float hi) { const f32x2 v = {lo, hi}; return __builtin_bit_cast(unsigned, __builtin_convertvector(v, bfx2_t)); }
; __device__ __forceinline__ float bflo(unsigned w) { return __uint_as_float(w << 16); }
; template <int PASS> __device__ void ssm_pass(const Params& P, int l, LAS unsigned char* lds) {
;     ...
;             u32x2 unext = ucur; if (mt < 63) unext = *(const u32x2*)(zrow + (size_t)(mt + 1) * 16 * DM);
;             const bf16x4 af = __builtin_bit_cast(bf16x4, ucur);
;             f32x4 d[8];
; #pragma unroll
;             for (int t = 0; t < 8; ++t) d[t] = __builtin_amdgcn_mfma_f32_16x16x16bf16_1k(af, bf[t], (f32x4){0.f, 0.f, 0.f, 0.f}, 0, 0, 0);
; #pragma unroll
;             for (int tq = 0; tq < 4; ++tq)
; #pragma unroll
;                 for (int j = 0; j < 4; ++j) *(LAS f32x2*)(BU + (4 * fq + j) * 528 + (16 * tq + fr) * 8) = (f32x2){d[tq][j], d[tq + 4][j]};
;             asm volatile("s_waitcnt lgkmcnt(0)" ::: "memory");
; #pragma unroll
;             for (int j = 0; j < 16; ++j) {
;                 const f32x2 bu = *(const LAS f32x2*)(BU + j * 528 + lane * 8);
;                 sv = __builtin_elementwise_fma(ayn, __builtin_shufflevector(sv, sv, 1, 0), __builtin_elementwise_fma(axx, sv, bu));
;                 if (PASS == 2) *(LAS unsigned*)(SI + j * 272 + lane * 4) = cvt_pk_bf16(sv.x, sv.y);
;             }
;             if (PASS == 2) {
;                 asm volatile("s_waitcnt lgkmcnt(0)" ::: "memory");
;                 f32x4 acc = (f32x4){0.f, 0.f, 0.f, 0.f};
; #pragma unroll
;                 for (int kt = 0; kt < 4; ++kt) { const bf16x8 sv = *(const LAS bf16x8*)(SI + fr * 272 + (32 * kt + 8 * fq) * 2);
;                     acc = __builtin_amdgcn_mfma_f32_16x16x32_bf16(cf[kt], sv, acc, 0, 0, 0); }
;                 const size_t tok = tok0 + 16 * mt + fr;
;                 float o[4];
;                 const float uf[4] = {bflo(ucur.x), bfhi(ucur.x), bflo(ucur.y), bfhi(ucur.y)};
; #pragma unroll
;                 for (int j = 0; j < 4; ++j) { const float y = acc[j] + dd[j] * uf[j]; o[j] = y * fsigmoid(1.5957691216057308f * (y + 0.044715f * y * y * y)); }
;                 u32x2 w; w.x = cvt_pk_bf16(o[0], o[1]); w.y = cvt_pk_bf16(o[2], o[3]);
;                 *(u32x2*)(ypre + tok * 512 + g * 16 + 4 * fq) = w;
;             }
	ds_write_b64 v146, v[140:141]
	ds_read_b128 v[192:195], v69 offset:8448
	ds_read_b128 v[204:207], v69 offset:8512
	ds_read_b128 v[212:215], v69 offset:8576
	ds_read_b128 v[216:219], v69 offset:8640
	ds_read_b128 v[156:159], v196
	ds_read_b128 v[200:203], v197
	global_load_dwordx2 v[62:63], v[60:61], off nt
	v_lshl_add_u64 v[60:61], v[60:61], 0, s[18:19]
	v_fma_f32 v70, v56, v54, v120
	v_fma_f32 v71, v56, v55, v226
	v_lshlrev_b32_e32 v76, 16, v136
	v_fma_f32 v72, v36, v55, v70
	v_fma_f32 v73, v37, v54, v71
	v_cvt_pk_bf16_f32 v74, v72, v73
	v_and_b32_e32 v77, 0xffff0000, v136
	v_fma_f32 v70, v56, v72, v121
	v_fma_f32 v71, v56, v73, v227
	v_lshlrev_b32_e32 v78, 16, v137
	v_fma_f32 v54, v36, v73, v70
	v_fma_f32 v55, v37, v72, v71
	v_cvt_pk_bf16_f32 v75, v54, v55
	v_and_b32_e32 v79, 0xffff0000, v137
	ds_write2_b32 v242, v74, v75 offset0:0 offset1:68
	s_waitcnt lgkmcnt(3)
	v_mfma_f32_16x16x32_bf16 v[220:223], v[0:3], v[192:195], 0
	v_mfma_f32_16x16x32_bf16 v[220:223], v[4:7], v[204:207], v[220:223]
	v_mfma_f32_16x16x32_bf16 v[220:223], v[8:11], v[212:215], v[220:223]
	v_mfma_f32_16x16x32_bf16 v[220:223], v[12:15], v[216:219], v[220:223]
	v_fma_f32 v70, v56, v54, v122
	v_fma_f32 v71, v56, v55, v228
	v_fma_f32 v72, v36, v55, v70
	v_fma_f32 v73, v37, v54, v71
	v_cvt_pk_bf16_f32 v74, v72, v73
	v_fma_f32 v70, v56, v72, v123
	v_fma_f32 v71, v56, v73, v229
	v_fma_f32 v54, v36, v73, v70
	v_fma_f32 v55, v37, v72, v71
	v_cvt_pk_bf16_f32 v75, v54, v55
	ds_write2_b32 v242, v74, v75 offset0:136 offset1:204
	s_waitcnt lgkmcnt(2)
	v_mfma_f32_32x32x16_bf16 v[88:103], v[156:159], v[38:41], 0
	v_mfma_f32_32x32x16_bf16 v[104:119], v[156:159], v[46:49], 0
	v_fma_f32 v70, v56, v54, v124
	v_fma_f32 v71, v56, v55, v230
	v_fma_f32 v80, v16, v76, v220
	v_fma_f32 v81, v17, v77, v221
	v_fma_f32 v72, v36, v55, v70
	v_fma_f32 v73, v37, v54, v71
	v_cvt_pk_bf16_f32 v74, v72, v73
	v_fma_f32 v82, v18, v78, v222
	v_fma_f32 v83, v19, v79, v223
	v_fma_f32 v70, v56, v72, v125
	v_fma_f32 v71, v56, v73, v231
	v_mul_f32_e32 v84, 0x3d372713, v80
	v_mul_f32_e32 v85, 0x3d372713, v81
	v_fma_f32 v54, v36, v73, v70
	v_fma_f32 v55, v37, v72, v71
	v_cvt_pk_bf16_f32 v75, v54, v55
	v_mul_f32_e32 v86, 0x3d372713, v82
	v_mul_f32_e32 v87, 0x3d372713, v83
	ds_write2_b32 v243, v74, v75 offset0:0 offset1:68
	v_mfma_f32_32x32x16_bf16 v[88:103], v[200:203], v[42:45], v[88:103]
	v_mfma_f32_32x32x16_bf16 v[104:119], v[200:203], v[50:53], v[104:119]
	v_fma_f32 v70, v56, v54, v126
	v_fma_f32 v71, v56, v55, v232
	v_mul_f32_e32 v84, v80, v84
	v_mul_f32_e32 v85, v81, v85
	v_fma_f32 v72, v36, v55, v70
	v_fma_f32 v73, v37, v54, v71
	v_cvt_pk_bf16_f32 v74, v72, v73
	v_mul_f32_e32 v86, v82, v86
	v_mul_f32_e32 v87, v83, v87
	v_fma_f32 v70, v56, v72, v127
	v_fma_f32 v71, v56, v73, v233
	v_fma_f32 v84, v80, v84, v80
	v_fma_f32 v85, v81, v85, v81
	v_fma_f32 v54, v36, v73, v70
	v_fma_f32 v55, v37, v72, v71
	v_cvt_pk_bf16_f32 v75, v54, v55
	v_fma_f32 v86, v82, v86, v82
	v_fma_f32 v87, v83, v87, v83
	ds_write2_b32 v243, v74, v75 offset0:136 offset1:204
	v_fma_f32 v70, v56, v54, v128
	v_fma_f32 v71, v56, v55, v234
	v_mul_f32_e32 v84, 0x3fcc422a, v84
	v_mul_f32_e32 v85, 0x3fcc422a, v85
	v_fma_f32 v72, v36, v55, v70
	v_fma_f32 v73, v37, v54, v71
	v_cvt_pk_bf16_f32 v74, v72, v73
	v_mul_f32_e32 v86, 0x3fcc422a, v86
	v_mul_f32_e32 v87, 0x3fcc422a, v87
	v_fma_f32 v70, v56, v72, v129
	v_fma_f32 v71, v56, v73, v235
	v_mul_f32_e32 v84, 0xbfb8aa3b, v84
	v_mul_f32_e32 v85, 0xbfb8aa3b, v85
	v_fma_f32 v54, v36, v73, v70
	v_fma_f32 v55, v37, v72, v71
	v_cvt_pk_bf16_f32 v75, v54, v55
	v_mul_f32_e32 v86, 0xbfb8aa3b, v86
	ds_write2_b32 v244, v74, v75 offset0:0 offset1:68
	v_fma_f32 v70, v56, v54, v130
	v_fma_f32 v71, v56, v55, v236
	v_mul_f32_e32 v87, 0xbfb8aa3b, v87
	v_exp_f32_e32 v84, v84
	v_fma_f32 v72, v36, v55, v70
	v_fma_f32 v73, v37, v54, v71
	v_cvt_pk_bf16_f32 v74, v72, v73
	v_exp_f32_e32 v85, v85
	v_exp_f32_e32 v86, v86
	v_fma_f32 v70, v56, v72, v131
	v_fma_f32 v71, v56, v73, v237
	v_exp_f32_e32 v87, v87
	v_add_f32_e32 v84, 1.0, v84
	v_fma_f32 v54, v36, v73, v70
	v_fma_f32 v55, v37, v72, v71
	v_cvt_pk_bf16_f32 v75, v54, v55
	v_add_f32_e32 v85, 1.0, v85
	ds_write2_b32 v244, v74, v75 offset0:136 offset1:204
	v_fma_f32 v70, v56, v54, v132
	v_fma_f32 v71, v56, v55, v238
	v_add_f32_e32 v86, 1.0, v86
	v_add_f32_e32 v87, 1.0, v87
	v_fma_f32 v72, v36, v55, v70
	v_fma_f32 v73, v37, v54, v71
	v_cvt_pk_bf16_f32 v74, v72, v73
	v_rcp_f32_e32 v84, v84
	v_rcp_f32_e32 v85, v85
	v_fma_f32 v70, v56, v72, v133
	v_fma_f32 v71, v56, v73, v239
	v_rcp_f32_e32 v86, v86
	v_rcp_f32_e32 v87, v87
	v_fma_f32 v54, v36, v73, v70
	v_fma_f32 v55, v37, v72, v71
	v_cvt_pk_bf16_f32 v75, v54, v55
	s_nop 0
	ds_write2_b32 v245, v74, v75 offset0:0 offset1:68
	v_fma_f32 v70, v56, v54, v134
	v_fma_f32 v71, v56, v55, v240
	v_mul_f32_e32 v84, v80, v84
	v_mul_f32_e32 v85, v81, v85
	v_fma_f32 v72, v36, v55, v70
	v_fma_f32 v73, v37, v54, v71
	v_cvt_pk_bf16_f32 v74, v72, v73
	v_mul_f32_e32 v86, v82, v86
	v_mul_f32_e32 v87, v83, v87
	v_fma_f32 v70, v56, v72, v135
	v_fma_f32 v71, v56, v73, v241
	v_cvt_pk_bf16_f32 v84, v84, v85
	v_fma_f32 v54, v36, v73, v70
	v_fma_f32 v55, v37, v72, v71
	v_cvt_pk_bf16_f32 v75, v54, v55
	v_cvt_pk_bf16_f32 v85, v86, v87
	ds_write2_b32 v245, v74, v75 offset0:136 offset1:204
	global_store_dwordx2 v[246:247], v[84:85], off
	s_mov_b64 s[18:19], 0x4000
	v_lshl_add_u64 v[246:247], v[246:247], 0, s[18:19]
	s_mov_b64 s[18:19], 0x8000
	s_waitcnt vmcnt(9)
; #define LAS __attribute__((address_space(3)))
; __device__ __forceinline__ unsigned cvt_pk_bf16(float lo, float hi) { const f32x2 v = {lo, hi}; return __builtin_bit_cast(unsigned, __builtin_convertvector(v, bfx2_t)); }
; __device__ __forceinline__ float bflo(unsigned w) { return __uint_as_float(w << 16); }
; template <int PASS> __device__ void ssm_pass(const Params& P, int l, LAS unsigned char* lds) {
;     ...
;             u32x2 unext = ucur; if (mt < 63) unext = *(const u32x2*)(zrow + (size_t)(mt + 1) * 16 * DM);
;             const bf16x4 af = __builtin_bit_cast(bf16x4, ucur);
;             f32x4 d[8];
; #pragma unroll
;             for (int t = 0; t < 8; ++t) d[t] = __builtin_amdgcn_mfma_f32_16x16x16bf16_1k(af, bf[t], (f32x4){0.f, 0.f, 0.f, 0.f}, 0, 0, 0);
; #pragma unroll
;             for (int tq = 0; tq < 4; ++tq)
; #pragma unroll
;                 for (int j = 0; j < 4; ++j) *(LAS f32x2*)(BU + (4 * fq + j) * 528 + (16 * tq + fr) * 8) = (f32x2){d[tq][j], d[tq + 4][j]};
;             asm volatile("s_waitcnt lgkmcnt(0)" ::: "memory");
; #pragma unroll
;             for (int j = 0; j < 16; ++j) {
;                 const f32x2 bu = *(const LAS f32x2*)(BU + j * 528 + lane * 8);
;                 sv = __builtin_elementwise_fma(ayn, __builtin_shufflevector(sv, sv, 1, 0), __builtin_elementwise_fma(axx, sv, bu));
;                 if (PASS == 2) *(LAS unsigned*)(SI + j * 272 + lane * 4) = cvt_pk_bf16(sv.x, sv.y);
;             }
;             if (PASS == 2) {
;                 asm volatile("s_waitcnt lgkmcnt(0)" ::: "memory");
;                 f32x4 acc = (f32x4){0.f, 0.f, 0.f, 0.f};
; #pragma unroll
;                 for (int kt = 0; kt < 4; ++kt) { const bf16x8 sv = *(const LAS bf16x8*)(SI + fr * 272 + (32 * kt + 8 * fq) * 2);
;                     acc = __builtin_amdgcn_mfma_f32_16x16x32_bf16(cf[kt], sv, acc, 0, 0, 0); }
;                 const size_t tok = tok0 + 16 * mt + fr;
;                 float o[4];
;                 const float uf[4] = {bflo(ucur.x), bfhi(ucur.x), bflo(ucur.y), bfhi(ucur.y)};
; #pragma unroll
;                 for (int j = 0; j < 4; ++j) { const float y = acc[j] + dd[j] * uf[j]; o[j] = y * fsigmoid(1.5957691216057308f * (y + 0.044715f * y * y * y)); }
;                 u32x2 w; w.x = cvt_pk_bf16(o[0], o[1]); w.y = cvt_pk_bf16(o[2], o[3]);
;                 *(u32x2*)(ypre + tok * 512 + g * 16 + 4 * fq) = w;
;             }
	ds_write_b64 v146, v[142:143]
	ds_read_b128 v[192:195], v69 offset:8448
	ds_read_b128 v[204:207], v69 offset:8512
	ds_read_b128 v[212:215], v69 offset:8576
	ds_read_b128 v[216:219], v69 offset:8640
	ds_read_b128 v[156:159], v196
	ds_read_b128 v[200:203], v197
	global_load_dwordx2 v[136:137], v[60:61], off nt
	v_lshl_add_u64 v[60:61], v[60:61], 0, s[18:19]
	v_fma_f32 v70, v56, v54, v88
	v_fma_f32 v71, v56, v55, v104
	v_lshlrev_b32_e32 v76, 16, v138
	v_fma_f32 v72, v36, v55, v70
	v_fma_f32 v73, v37, v54, v71
	v_cvt_pk_bf16_f32 v74, v72, v73
	v_and_b32_e32 v77, 0xffff0000, v138
	v_fma_f32 v70, v56, v72, v89
	v_fma_f32 v71, v56, v73, v105
	v_lshlrev_b32_e32 v78, 16, v139
	v_fma_f32 v54, v36, v73, v70
	v_fma_f32 v55, v37, v72, v71
	v_cvt_pk_bf16_f32 v75, v54, v55
	v_and_b32_e32 v79, 0xffff0000, v139
	ds_write2_b32 v242, v74, v75 offset0:0 offset1:68
	s_waitcnt lgkmcnt(3)
	v_mfma_f32_16x16x32_bf16 v[220:223], v[0:3], v[192:195], 0
	v_mfma_f32_16x16x32_bf16 v[220:223], v[4:7], v[204:207], v[220:223]
	v_mfma_f32_16x16x32_bf16 v[220:223], v[8:11], v[212:215], v[220:223]
	v_mfma_f32_16x16x32_bf16 v[220:223], v[12:15], v[216:219], v[220:223]
	v_fma_f32 v70, v56, v54, v90
	v_fma_f32 v71, v56, v55, v106
	v_fma_f32 v72, v36, v55, v70
	v_fma_f32 v73, v37, v54, v71
	v_cvt_pk_bf16_f32 v74, v72, v73
	v_fma_f32 v70, v56, v72, v91
	v_fma_f32 v71, v56, v73, v107
	v_fma_f32 v54, v36, v73, v70
	v_fma_f32 v55, v37, v72, v71
	v_cvt_pk_bf16_f32 v75, v54, v55
	ds_write2_b32 v242, v74, v75 offset0:136 offset1:204
	s_waitcnt lgkmcnt(2)
	v_mfma_f32_32x32x16_bf16 v[120:135], v[156:159], v[38:41], 0
	v_mfma_f32_32x32x16_bf16 v[226:241], v[156:159], v[46:49], 0
	v_fma_f32 v70, v56, v54, v92
	v_fma_f32 v71, v56, v55, v108
	v_fma_f32 v80, v16, v76, v220
	v_fma_f32 v81, v17, v77, v221
	v_fma_f32 v72, v36, v55, v70
	v_fma_f32 v73, v37, v54, v71
	v_cvt_pk_bf16_f32 v74, v72, v73
	v_fma_f32 v82, v18, v78, v222
	v_fma_f32 v83, v19, v79, v223
	v_fma_f32 v70, v56, v72, v93
	v_fma_f32 v71, v56, v73, v109
	v_mul_f32_e32 v84, 0x3d372713, v80
	v_mul_f32_e32 v85, 0x3d372713, v81
	v_fma_f32 v54, v36, v73, v70
	v_fma_f32 v55, v37, v72, v71
	v_cvt_pk_bf16_f32 v75, v54, v55
	v_mul_f32_e32 v86, 0x3d372713, v82
	v_mul_f32_e32 v87, 0x3d372713, v83
	ds_write2_b32 v243, v74, v75 offset0:0 offset1:68
	v_mfma_f32_32x32x16_bf16 v[120:135], v[200:203], v[42:45], v[120:135]
	v_mfma_f32_32x32x16_bf16 v[226:241], v[200:203], v[50:53], v[226:241]
	v_fma_f32 v70, v56, v54, v94
	v_fma_f32 v71, v56, v55, v110
	v_mul_f32_e32 v84, v80, v84
	v_mul_f32_e32 v85, v81, v85
	v_fma_f32 v72, v36, v55, v70
	v_fma_f32 v73, v37, v54, v71
	v_cvt_pk_bf16_f32 v74, v72, v73
	v_mul_f32_e32 v86, v82, v86
	v_mul_f32_e32 v87, v83, v87
	v_fma_f32 v70, v56, v72, v95
	v_fma_f32 v71, v56, v73, v111
	v_fma_f32 v84, v80, v84, v80
	v_fma_f32 v85, v81, v85, v81
	v_fma_f32 v54, v36, v73, v70
	v_fma_f32 v55, v37, v72, v71
	v_cvt_pk_bf16_f32 v75, v54, v55
	v_fma_f32 v86, v82, v86, v82
	v_fma_f32 v87, v83, v87, v83
	ds_write2_b32 v243, v74, v75 offset0:136 offset1:204
	v_fma_f32 v70, v56, v54, v96
	v_fma_f32 v71, v56, v55, v112
	v_mul_f32_e32 v84, 0x3fcc422a, v84
	v_mul_f32_e32 v85, 0x3fcc422a, v85
	v_fma_f32 v72, v36, v55, v70
	v_fma_f32 v73, v37, v54, v71
	v_cvt_pk_bf16_f32 v74, v72, v73
	v_mul_f32_e32 v86, 0x3fcc422a, v86
	v_mul_f32_e32 v87, 0x3fcc422a, v87
	v_fma_f32 v70, v56, v72, v97
	v_fma_f32 v71, v56, v73, v113
	v_mul_f32_e32 v84, 0xbfb8aa3b, v84
	v_mul_f32_e32 v85, 0xbfb8aa3b, v85
	v_fma_f32 v54, v36, v73, v70
	v_fma_f32 v55, v37, v72, v71
	v_cvt_pk_bf16_f32 v75, v54, v55
	v_mul_f32_e32 v86, 0xbfb8aa3b, v86
	ds_write2_b32 v244, v74, v75 offset0:0 offset1:68
	v_fma_f32 v70, v56, v54, v98
	v_fma_f32 v71, v56, v55, v114
	v_mul_f32_e32 v87, 0xbfb8aa3b, v87
	v_exp_f32_e32 v84, v84
	v_fma_f32 v72, v36, v55, v70
	v_fma_f32 v73, v37, v54, v71
	v_cvt_pk_bf16_f32 v74, v72, v73
	v_exp_f32_e32 v85, v85
	v_exp_f32_e32 v86, v86
	v_fma_f32 v70, v56, v72, v99
	v_fma_f32 v71, v56, v73, v115
	v_exp_f32_e32 v87, v87
	v_add_f32_e32 v84, 1.0, v84
	v_fma_f32 v54, v36, v73, v70
	v_fma_f32 v55, v37, v72, v71
	v_cvt_pk_bf16_f32 v75, v54, v55
	v_add_f32_e32 v85, 1.0, v85
	ds_write2_b32 v244, v74, v75 offset0:136 offset1:204
	v_fma_f32 v70, v56, v54, v100
	v_fma_f32 v71, v56, v55, v116
	v_add_f32_e32 v86, 1.0, v86
	v_add_f32_e32 v87, 1.0, v87
	v_fma_f32 v72, v36, v55, v70
	v_fma_f32 v73, v37, v54, v71
	v_cvt_pk_bf16_f32 v74, v72, v73
	v_rcp_f32_e32 v84, v84
	v_rcp_f32_e32 v85, v85
	v_fma_f32 v70, v56, v72, v101
	v_fma_f32 v71, v56, v73, v117
	v_rcp_f32_e32 v86, v86
	v_rcp_f32_e32 v87, v87
	v_fma_f32 v54, v36, v73, v70
	v_fma_f32 v55, v37, v72, v71
	v_cvt_pk_bf16_f32 v75, v54, v55
	s_nop 0
	ds_write2_b32 v245, v74, v75 offset0:0 offset1:68
	v_fma_f32 v70, v56, v54, v102
	v_fma_f32 v71, v56, v55, v118
	v_mul_f32_e32 v84, v80, v84
	v_mul_f32_e32 v85, v81, v85
	v_fma_f32 v72, v36, v55, v70
	v_fma_f32 v73, v37, v54, v71
	v_cvt_pk_bf16_f32 v74, v72, v73
	v_mul_f32_e32 v86, v82, v86
	v_mul_f32_e32 v87, v83, v87
	v_fma_f32 v70, v56, v72, v103
	v_fma_f32 v71, v56, v73, v119
	v_cvt_pk_bf16_f32 v84, v84, v85
	v_fma_f32 v54, v36, v73, v70
	v_fma_f32 v55, v37, v72, v71
	v_cvt_pk_bf16_f32 v75, v54, v55
	v_cvt_pk_bf16_f32 v85, v86, v87
	ds_write2_b32 v245, v74, v75 offset0:136 offset1:204
	global_store_dwordx2 v[246:247], v[84:85], off
	s_mov_b64 s[18:19], 0x4000
	v_lshl_add_u64 v[246:247], v[246:247], 0, s[18:19]
	s_mov_b64 s[18:19], 0x8000
	s_waitcnt vmcnt(9)
; #define LAS __attribute__((address_space(3)))
; __device__ __forceinline__ unsigned cvt_pk_bf16(float lo, float hi) { const f32x2 v = {lo, hi}; return __builtin_bit_cast(unsigned, __builtin_convertvector(v, bfx2_t)); }
; __device__ __forceinline__ float bflo(unsigned w) { return __uint_as_float(w << 16); }
; template <int PASS> __device__ void ssm_pass(const Params& P, int l, LAS unsigned char* lds) {
;     ...
;             u32x2 unext = ucur; if (mt < 63) unext = *(const u32x2*)(zrow + (size_t)(mt + 1) * 16 * DM);
;             const bf16x4 af = __builtin_bit_cast(bf16x4, ucur);
;             f32x4 d[8];
; #pragma unroll
;             for (int t = 0; t < 8; ++t) d[t] = __builtin_amdgcn_mfma_f32_16x16x16bf16_1k(af, bf[t], (f32x4){0.f, 0.f, 0.f, 0.f}, 0, 0, 0);
; #pragma unroll
;             for (int tq = 0; tq < 4; ++tq)
; #pragma unroll
;                 for (int j = 0; j < 4; ++j) *(LAS f32x2*)(BU + (4 * fq + j) * 528 + (16 * tq + fr) * 8) = (f32x2){d[tq][j], d[tq + 4][j]};
;             asm volatile("s_waitcnt lgkmcnt(0)" ::: "memory");
; #pragma unroll
;             for (int j = 0; j < 16; ++j) {
;                 const f32x2 bu = *(const LAS f32x2*)(BU + j * 528 + lane * 8);
;                 sv = __builtin_elementwise_fma(ayn, __builtin_shufflevector(sv, sv, 1, 0), __builtin_elementwise_fma(axx, sv, bu));
;                 if (PASS == 2) *(LAS unsigned*)(SI + j * 272 + lane * 4) = cvt_pk_bf16(sv.x, sv.y);
;             }
;             if (PASS == 2) {
;                 asm volatile("s_waitcnt lgkmcnt(0)" ::: "memory");
;                 f32x4 acc = (f32x4){0.f, 0.f, 0.f, 0.f};
; #pragma unroll
;                 for (int kt = 0; kt < 4; ++kt) { const bf16x8 sv = *(const LAS bf16x8*)(SI + fr * 272 + (32 * kt + 8 * fq) * 2);
;                     acc = __builtin_amdgcn_mfma_f32_16x16x32_bf16(cf[kt], sv, acc, 0, 0, 0); }
;                 const size_t tok = tok0 + 16 * mt + fr;
;                 float o[4];
;                 const float uf[4] = {bflo(ucur.x), bfhi(ucur.x), bflo(ucur.y), bfhi(ucur.y)};
; #pragma unroll
;                 for (int j = 0; j < 4; ++j) { const float y = acc[j] + dd[j] * uf[j]; o[j] = y * fsigmoid(1.5957691216057308f * (y + 0.044715f * y * y * y)); }
;                 u32x2 w; w.x = cvt_pk_bf16(o[0], o[1]); w.y = cvt_pk_bf16(o[2], o[3]);
;                 *(u32x2*)(ypre + tok * 512 + g * 16 + 4 * fq) = w;
;             }
	ds_write_b64 v146, v[144:145]
	ds_read_b128 v[192:195], v69 offset:8448
	ds_read_b128 v[204:207], v69 offset:8512
	ds_read_b128 v[212:215], v69 offset:8576
	ds_read_b128 v[216:219], v69 offset:8640
	ds_read_b128 v[156:159], v196
	ds_read_b128 v[200:203], v197
	global_load_dwordx2 v[138:139], v[60:61], off nt
	v_lshl_add_u64 v[60:61], v[60:61], 0, s[18:19]
	v_fma_f32 v70, v56, v54, v120
	v_fma_f32 v71, v56, v55, v226
	v_lshlrev_b32_e32 v76, 16, v140
	v_fma_f32 v72, v36, v55, v70
	v_fma_f32 v73, v37, v54, v71
	v_cvt_pk_bf16_f32 v74, v72, v73
	v_and_b32_e32 v77, 0xffff0000, v140
	v_fma_f32 v70, v56, v72, v121
	v_fma_f32 v71, v56, v73, v227
	v_lshlrev_b32_e32 v78, 16, v141
	v_fma_f32 v54, v36, v73, v70
	v_fma_f32 v55, v37, v72, v71
	v_cvt_pk_bf16_f32 v75, v54, v55
	v_and_b32_e32 v79, 0xffff0000, v141
	ds_write2_b32 v242, v74, v75 offset0:0 offset1:68
	s_waitcnt lgkmcnt(3)
	v_mfma_f32_16x16x32_bf16 v[220:223], v[0:3], v[192:195], 0
	v_mfma_f32_16x16x32_bf16 v[220:223], v[4:7], v[204:207], v[220:223]
	v_mfma_f32_16x16x32_bf16 v[220:223], v[8:11], v[212:215], v[220:223]
	v_mfma_f32_16x16x32_bf16 v[220:223], v[12:15], v[216:219], v[220:223]
	v_fma_f32 v70, v56, v54, v122
	v_fma_f32 v71, v56, v55, v228
	v_fma_f32 v72, v36, v55, v70
	v_fma_f32 v73, v37, v54, v71
	v_cvt_pk_bf16_f32 v74, v72, v73
	v_fma_f32 v70, v56, v72, v123
	v_fma_f32 v71, v56, v73, v229
	v_fma_f32 v54, v36, v73, v70
	v_fma_f32 v55, v37, v72, v71
	v_cvt_pk_bf16_f32 v75, v54, v55
	ds_write2_b32 v242, v74, v75 offset0:136 offset1:204
	s_waitcnt lgkmcnt(2)
	v_mfma_f32_32x32x16_bf16 v[88:103], v[156:159], v[38:41], 0
	v_mfma_f32_32x32x16_bf16 v[104:119], v[156:159], v[46:49], 0
	v_fma_f32 v70, v56, v54, v124
	v_fma_f32 v71, v56, v55, v230
	v_fma_f32 v80, v16, v76, v220
	v_fma_f32 v81, v17, v77, v221
	v_fma_f32 v72, v36, v55, v70
	v_fma_f32 v73, v37, v54, v71
	v_cvt_pk_bf16_f32 v74, v72, v73
	v_fma_f32 v82, v18, v78, v222
	v_fma_f32 v83, v19, v79, v223
	v_fma_f32 v70, v56, v72, v125
	v_fma_f32 v71, v56, v73, v231
	v_mul_f32_e32 v84, 0x3d372713, v80
	v_mul_f32_e32 v85, 0x3d372713, v81
	v_fma_f32 v54, v36, v73, v70
	v_fma_f32 v55, v37, v72, v71
	v_cvt_pk_bf16_f32 v75, v54, v55
	v_mul_f32_e32 v86, 0x3d372713, v82
	v_mul_f32_e32 v87, 0x3d372713, v83
	ds_write2_b32 v243, v74, v75 offset0:0 offset1:68
	v_mfma_f32_32x32x16_bf16 v[88:103], v[200:203], v[42:45], v[88:103]
	v_mfma_f32_32x32x16_bf16 v[104:119], v[200:203], v[50:53], v[104:119]
	v_fma_f32 v70, v56, v54, v126
	v_fma_f32 v71, v56, v55, v232
	v_mul_f32_e32 v84, v80, v84
	v_mul_f32_e32 v85, v81, v85
	v_fma_f32 v72, v36, v55, v70
	v_fma_f32 v73, v37, v54, v71
	v_cvt_pk_bf16_f32 v74, v72, v73
	v_mul_f32_e32 v86, v82, v86
	v_mul_f32_e32 v87, v83, v87
	v_fma_f32 v70, v56, v72, v127
	v_fma_f32 v71, v56, v73, v233
	v_fma_f32 v84, v80, v84, v80
	v_fma_f32 v85, v81, v85, v81
	v_fma_f32 v54, v36, v73, v70
	v_fma_f32 v55, v37, v72, v71
	v_cvt_pk_bf16_f32 v75, v54, v55
	v_fma_f32 v86, v82, v86, v82
	v_fma_f32 v87, v83, v87, v83
	ds_write2_b32 v243, v74, v75 offset0:136 offset1:204
	v_fma_f32 v70, v56, v54, v128
	v_fma_f32 v71, v56, v55, v234
	v_mul_f32_e32 v84, 0x3fcc422a, v84
	v_mul_f32_e32 v85, 0x3fcc422a, v85
	v_fma_f32 v72, v36, v55, v70
	v_fma_f32 v73, v37, v54, v71
	v_cvt_pk_bf16_f32 v74, v72, v73
	v_mul_f32_e32 v86, 0x3fcc422a, v86
	v_mul_f32_e32 v87, 0x3fcc422a, v87
	v_fma_f32 v70, v56, v72, v129
	v_fma_f32 v71, v56, v73, v235
	v_mul_f32_e32 v84, 0xbfb8aa3b, v84
	v_mul_f32_e32 v85, 0xbfb8aa3b, v85
	v_fma_f32 v54, v36, v73, v70
	v_fma_f32 v55, v37, v72, v71
	v_cvt_pk_bf16_f32 v75, v54, v55
	v_mul_f32_e32 v86, 0xbfb8aa3b, v86
	ds_write2_b32 v244, v74, v75 offset0:0 offset1:68
	v_fma_f32 v70, v56, v54, v130
	v_fma_f32 v71, v56, v55, v236
	v_mul_f32_e32 v87, 0xbfb8aa3b, v87
	v_exp_f32_e32 v84, v84
	v_fma_f32 v72, v36, v55, v70
	v_fma_f32 v73, v37, v54, v71
	v_cvt_pk_bf16_f32 v74, v72, v73
	v_exp_f32_e32 v85, v85
	v_exp_f32_e32 v86, v86
	v_fma_f32 v70, v56, v72, v131
	v_fma_f32 v71, v56, v73, v237
	v_exp_f32_e32 v87, v87
	v_add_f32_e32 v84, 1.0, v84
	v_fma_f32 v54, v36, v73, v70
	v_fma_f32 v55, v37, v72, v71
	v_cvt_pk_bf16_f32 v75, v54, v55
	v_add_f32_e32 v85, 1.0, v85
	ds_write2_b32 v244, v74, v75 offset0:136 offset1:204
	v_fma_f32 v70, v56, v54, v132
	v_fma_f32 v71, v56, v55, v238
	v_add_f32_e32 v86, 1.0, v86
	v_add_f32_e32 v87, 1.0, v87
	v_fma_f32 v72, v36, v55, v70
	v_fma_f32 v73, v37, v54, v71
	v_cvt_pk_bf16_f32 v74, v72, v73
	v_rcp_f32_e32 v84, v84
	v_rcp_f32_e32 v85, v85
	v_fma_f32 v70, v56, v72, v133
	v_fma_f32 v71, v56, v73, v239
	v_rcp_f32_e32 v86, v86
	v_rcp_f32_e32 v87, v87
	v_fma_f32 v54, v36, v73, v70
	v_fma_f32 v55, v37, v72, v71
	v_cvt_pk_bf16_f32 v75, v54, v55
	s_nop 0
	ds_write2_b32 v245, v74, v75 offset0:0 offset1:68
	v_fma_f32 v70, v56, v54, v134
	v_fma_f32 v71, v56, v55, v240
	v_mul_f32_e32 v84, v80, v84
	v_mul_f32_e32 v85, v81, v85
	v_fma_f32 v72, v36, v55, v70
	v_fma_f32 v73, v37, v54, v71
	v_cvt_pk_bf16_f32 v74, v72, v73
	v_mul_f32_e32 v86, v82, v86
	v_mul_f32_e32 v87, v83, v87
	v_fma_f32 v70, v56, v72, v135
	v_fma_f32 v71, v56, v73, v241
	v_cvt_pk_bf16_f32 v84, v84, v85
	v_fma_f32 v54, v36, v73, v70
	v_fma_f32 v55, v37, v72, v71
	v_cvt_pk_bf16_f32 v75, v54, v55
	v_cvt_pk_bf16_f32 v85, v86, v87
	ds_write2_b32 v245, v74, v75 offset0:136 offset1:204
	global_store_dwordx2 v[246:247], v[84:85], off
	s_mov_b64 s[18:19], 0x4000
	v_lshl_add_u64 v[246:247], v[246:247], 0, s[18:19]
	s_mov_b64 s[18:19], 0x8000
	s_waitcnt vmcnt(9)
; #define LAS __attribute__((address_space(3)))
; __device__ __forceinline__ unsigned cvt_pk_bf16(float lo, float hi) { const f32x2 v = {lo, hi}; return __builtin_bit_cast(unsigned, __builtin_convertvector(v, bfx2_t)); }
; __device__ __forceinline__ float bflo(unsigned w) { return __uint_as_float(w << 16); }
; template <int PASS> __device__ void ssm_pass(const Params& P, int l, LAS unsigned char* lds) {
;     ...
;             u32x2 unext = ucur; if (mt < 63) unext = *(const u32x2*)(zrow + (size_t)(mt + 1) * 16 * DM);
;             const bf16x4 af = __builtin_bit_cast(bf16x4, ucur);
;             f32x4 d[8];
; #pragma unroll
;             for (int t = 0; t < 8; ++t) d[t] = __builtin_amdgcn_mfma_f32_16x16x16bf16_1k(af, bf[t], (f32x4){0.f, 0.f, 0.f, 0.f}, 0, 0, 0);
; #pragma unroll
;             for (int tq = 0; tq < 4; ++tq)
; #pragma unroll
;                 for (int j = 0; j < 4; ++j) *(LAS f32x2*)(BU + (4 * fq + j) * 528 + (16 * tq + fr) * 8) = (f32x2){d[tq][j], d[tq + 4][j]};
;             asm volatile("s_waitcnt lgkmcnt(0)" ::: "memory");
; #pragma unroll
;             for (int j = 0; j < 16; ++j) {
;                 const f32x2 bu = *(const LAS f32x2*)(BU + j * 528 + lane * 8);
;                 sv = __builtin_elementwise_fma(ayn, __builtin_shufflevector(sv, sv, 1, 0), __builtin_elementwise_fma(axx, sv, bu));
;                 if (PASS == 2) *(LAS unsigned*)(SI + j * 272 + lane * 4) = cvt_pk_bf16(sv.x, sv.y);
;             }
;             if (PASS == 2) {
;                 asm volatile("s_waitcnt lgkmcnt(0)" ::: "memory");
;                 f32x4 acc = (f32x4){0.f, 0.f, 0.f, 0.f};
; #pragma unroll
;                 for (int kt = 0; kt < 4; ++kt) { const bf16x8 sv = *(const LAS bf16x8*)(SI + fr * 272 + (32 * kt + 8 * fq) * 2);
;                     acc = __builtin_amdgcn_mfma_f32_16x16x32_bf16(cf[kt], sv, acc, 0, 0, 0); }
;                 const size_t tok = tok0 + 16 * mt + fr;
;                 float o[4];
;                 const float uf[4] = {bflo(ucur.x), bfhi(ucur.x), bflo(ucur.y), bfhi(ucur.y)};
; #pragma unroll
;                 for (int j = 0; j < 4; ++j) { const float y = acc[j] + dd[j] * uf[j]; o[j] = y * fsigmoid(1.5957691216057308f * (y + 0.044715f * y * y * y)); }
;                 u32x2 w; w.x = cvt_pk_bf16(o[0], o[1]); w.y = cvt_pk_bf16(o[2], o[3]);
;                 *(u32x2*)(ypre + tok * 512 + g * 16 + 4 * fq) = w;
;             }
	ds_write_b64 v146, v[148:149]
	ds_read_b128 v[192:195], v69 offset:8448
	ds_read_b128 v[204:207], v69 offset:8512
	ds_read_b128 v[212:215], v69 offset:8576
	ds_read_b128 v[216:219], v69 offset:8640
	ds_read_b128 v[156:159], v196
	ds_read_b128 v[200:203], v197
	global_load_dwordx2 v[140:141], v[60:61], off nt
	v_lshl_add_u64 v[60:61], v[60:61], 0, s[18:19]
	v_fma_f32 v70, v56, v54, v88
	v_fma_f32 v71, v56, v55, v104
	v_lshlrev_b32_e32 v76, 16, v142
	v_fma_f32 v72, v36, v55, v70
	v_fma_f32 v73, v37, v54, v71
	v_cvt_pk_bf16_f32 v74, v72, v73
	v_and_b32_e32 v77, 0xffff0000, v142
	v_fma_f32 v70, v56, v72, v89
	v_fma_f32 v71, v56, v73, v105
	v_lshlrev_b32_e32 v78, 16, v143
	v_fma_f32 v54, v36, v73, v70
	v_fma_f32 v55, v37, v72, v71
	v_cvt_pk_bf16_f32 v75, v54, v55
	v_and_b32_e32 v79, 0xffff0000, v143
	ds_write2_b32 v242, v74, v75 offset0:0 offset1:68
	s_waitcnt lgkmcnt(3)
	v_mfma_f32_16x16x32_bf16 v[220:223], v[0:3], v[192:195], 0
	v_mfma_f32_16x16x32_bf16 v[220:223], v[4:7], v[204:207], v[220:223]
	v_mfma_f32_16x16x32_bf16 v[220:223], v[8:11], v[212:215], v[220:223]
	v_mfma_f32_16x16x32_bf16 v[220:223], v[12:15], v[216:219], v[220:223]
	v_fma_f32 v70, v56, v54, v90
	v_fma_f32 v71, v56, v55, v106
	v_fma_f32 v72, v36, v55, v70
	v_fma_f32 v73, v37, v54, v71
	v_cvt_pk_bf16_f32 v74, v72, v73
	v_fma_f32 v70, v56, v72, v91
	v_fma_f32 v71, v56, v73, v107
	v_fma_f32 v54, v36, v73, v70
	v_fma_f32 v55, v37, v72, v71
	v_cvt_pk_bf16_f32 v75, v54, v55
	ds_write2_b32 v242, v74, v75 offset0:136 offset1:204
	s_waitcnt lgkmcnt(2)
	v_mfma_f32_32x32x16_bf16 v[120:135], v[156:159], v[38:41], 0
	v_mfma_f32_32x32x16_bf16 v[226:241], v[156:159], v[46:49], 0
	v_fma_f32 v70, v56, v54, v92
	v_fma_f32 v71, v56, v55, v108
	v_fma_f32 v80, v16, v76, v220
	v_fma_f32 v81, v17, v77, v221
	v_fma_f32 v72, v36, v55, v70
	v_fma_f32 v73, v37, v54, v71
	v_cvt_pk_bf16_f32 v74, v72, v73
	v_fma_f32 v82, v18, v78, v222
	v_fma_f32 v83, v19, v79, v223
	v_fma_f32 v70, v56, v72, v93
	v_fma_f32 v71, v56, v73, v109
	v_mul_f32_e32 v84, 0x3d372713, v80
	v_mul_f32_e32 v85, 0x3d372713, v81
	v_fma_f32 v54, v36, v73, v70
	v_fma_f32 v55, v37, v72, v71
	v_cvt_pk_bf16_f32 v75, v54, v55
	v_mul_f32_e32 v86, 0x3d372713, v82
	v_mul_f32_e32 v87, 0x3d372713, v83
	ds_write2_b32 v243, v74, v75 offset0:0 offset1:68
	v_mfma_f32_32x32x16_bf16 v[120:135], v[200:203], v[42:45], v[120:135]
	v_mfma_f32_32x32x16_bf16 v[226:241], v[200:203], v[50:53], v[226:241]
	v_fma_f32 v70, v56, v54, v94
	v_fma_f32 v71, v56, v55, v110
	v_mul_f32_e32 v84, v80, v84
	v_mul_f32_e32 v85, v81, v85
	v_fma_f32 v72, v36, v55, v70
	v_fma_f32 v73, v37, v54, v71
	v_cvt_pk_bf16_f32 v74, v72, v73
	v_mul_f32_e32 v86, v82, v86
	v_mul_f32_e32 v87, v83, v87
	v_fma_f32 v70, v56, v72, v95
	v_fma_f32 v71, v56, v73, v111
	v_fma_f32 v84, v80, v84, v80
	v_fma_f32 v85, v81, v85, v81
	v_fma_f32 v54, v36, v73, v70
	v_fma_f32 v55, v37, v72, v71
	v_cvt_pk_bf16_f32 v75, v54, v55
	v_fma_f32 v86, v82, v86, v82
	v_fma_f32 v87, v83, v87, v83
	ds_write2_b32 v243, v74, v75 offset0:136 offset1:204
	v_fma_f32 v70, v56, v54, v96
	v_fma_f32 v71, v56, v55, v112
	v_mul_f32_e32 v84, 0x3fcc422a, v84
	v_mul_f32_e32 v85, 0x3fcc422a, v85
	v_fma_f32 v72, v36, v55, v70
	v_fma_f32 v73, v37, v54, v71
	v_cvt_pk_bf16_f32 v74, v72, v73
	v_mul_f32_e32 v86, 0x3fcc422a, v86
	v_mul_f32_e32 v87, 0x3fcc422a, v87
	v_fma_f32 v70, v56, v72, v97
	v_fma_f32 v71, v56, v73, v113
	v_mul_f32_e32 v84, 0xbfb8aa3b, v84
	v_mul_f32_e32 v85, 0xbfb8aa3b, v85
	v_fma_f32 v54, v36, v73, v70
	v_fma_f32 v55, v37, v72, v71
	v_cvt_pk_bf16_f32 v75, v54, v55
	v_mul_f32_e32 v86, 0xbfb8aa3b, v86
	ds_write2_b32 v244, v74, v75 offset0:0 offset1:68
	v_fma_f32 v70, v56, v54, v98
	v_fma_f32 v71, v56, v55, v114
	v_mul_f32_e32 v87, 0xbfb8aa3b, v87
	v_exp_f32_e32 v84, v84
	v_fma_f32 v72, v36, v55, v70
	v_fma_f32 v73, v37, v54, v71
	v_cvt_pk_bf16_f32 v74, v72, v73
	v_exp_f32_e32 v85, v85
	v_exp_f32_e32 v86, v86
	v_fma_f32 v70, v56, v72, v99
	v_fma_f32 v71, v56, v73, v115
	v_exp_f32_e32 v87, v87
	v_add_f32_e32 v84, 1.0, v84
	v_fma_f32 v54, v36, v73, v70
	v_fma_f32 v55, v37, v72, v71
	v_cvt_pk_bf16_f32 v75, v54, v55
	v_add_f32_e32 v85, 1.0, v85
	ds_write2_b32 v244, v74, v75 offset0:136 offset1:204
	v_fma_f32 v70, v56, v54, v100
	v_fma_f32 v71, v56, v55, v116
	v_add_f32_e32 v86, 1.0, v86
	v_add_f32_e32 v87, 1.0, v87
	v_fma_f32 v72, v36, v55, v70
	v_fma_f32 v73, v37, v54, v71
	v_cvt_pk_bf16_f32 v74, v72, v73
	v_rcp_f32_e32 v84, v84
	v_rcp_f32_e32 v85, v85
	v_fma_f32 v70, v56, v72, v101
	v_fma_f32 v71, v56, v73, v117
	v_rcp_f32_e32 v86, v86
	v_rcp_f32_e32 v87, v87
	v_fma_f32 v54, v36, v73, v70
	v_fma_f32 v55, v37, v72, v71
	v_cvt_pk_bf16_f32 v75, v54, v55
	s_nop 0
	ds_write2_b32 v245, v74, v75 offset0:0 offset1:68
	v_fma_f32 v70, v56, v54, v102
	v_fma_f32 v71, v56, v55, v118
	v_mul_f32_e32 v84, v80, v84
	v_mul_f32_e32 v85, v81, v85
	v_fma_f32 v72, v36, v55, v70
	v_fma_f32 v73, v37, v54, v71
	v_cvt_pk_bf16_f32 v74, v72, v73
	v_mul_f32_e32 v86, v82, v86
	v_mul_f32_e32 v87, v83, v87
	v_fma_f32 v70, v56, v72, v103
	v_fma_f32 v71, v56, v73, v119
	v_cvt_pk_bf16_f32 v84, v84, v85
	v_fma_f32 v54, v36, v73, v70
	v_fma_f32 v55, v37, v72, v71
	v_cvt_pk_bf16_f32 v75, v54, v55
	v_cvt_pk_bf16_f32 v85, v86, v87
	ds_write2_b32 v245, v74, v75 offset0:136 offset1:204
	global_store_dwordx2 v[246:247], v[84:85], off
	s_mov_b64 s[18:19], 0x4000
	v_lshl_add_u64 v[246:247], v[246:247], 0, s[18:19]
	s_mov_b64 s[18:19], 0x8000
	s_waitcnt vmcnt(9)
; #define LAS __attribute__((address_space(3)))
; __device__ __forceinline__ unsigned cvt_pk_bf16(float lo, float hi) { const f32x2 v = {lo, hi}; return __builtin_bit_cast(unsigned, __builtin_convertvector(v, bfx2_t)); }
; __device__ __forceinline__ float bflo(unsigned w) { return __uint_as_float(w << 16); }
; template <int PASS> __device__ void ssm_pass(const Params& P, int l, LAS unsigned char* lds) {
;     ...
;             u32x2 unext = ucur; if (mt < 63) unext = *(const u32x2*)(zrow + (size_t)(mt + 1) * 16 * DM);
;             const bf16x4 af = __builtin_bit_cast(bf16x4, ucur);
;             f32x4 d[8];
; #pragma unroll
;             for (int t = 0; t < 8; ++t) d[t] = __builtin_amdgcn_mfma_f32_16x16x16bf16_1k(af, bf[t], (f32x4){0.f, 0.f, 0.f, 0.f}, 0, 0, 0);
; #pragma unroll
;             for (int tq = 0; tq < 4; ++tq)
; #pragma unroll
;                 for (int j = 0; j < 4; ++j) *(LAS f32x2*)(BU + (4 * fq + j) * 528 + (16 * tq + fr) * 8) = (f32x2){d[tq][j], d[tq + 4][j]};
;             asm volatile("s_waitcnt lgkmcnt(0)" ::: "memory");
; #pragma unroll
;             for (int j = 0; j < 16; ++j) {
;                 const f32x2 bu = *(const LAS f32x2*)(BU + j * 528 + lane * 8);
;                 sv = __builtin_elementwise_fma(ayn, __builtin_shufflevector(sv, sv, 1, 0), __builtin_elementwise_fma(axx, sv, bu));
;                 if (PASS == 2) *(LAS unsigned*)(SI + j * 272 + lane * 4) = cvt_pk_bf16(sv.x, sv.y);
;             }
;             if (PASS == 2) {
;                 asm volatile("s_waitcnt lgkmcnt(0)" ::: "memory");
;                 f32x4 acc = (f32x4){0.f, 0.f, 0.f, 0.f};
; #pragma unroll
;                 for (int kt = 0; kt < 4; ++kt) { const bf16x8 sv = *(const LAS bf16x8*)(SI + fr * 272 + (32 * kt + 8 * fq) * 2);
;                     acc = __builtin_amdgcn_mfma_f32_16x16x32_bf16(cf[kt], sv, acc, 0, 0, 0); }
;                 const size_t tok = tok0 + 16 * mt + fr;
;                 float o[4];
;                 const float uf[4] = {bflo(ucur.x), bfhi(ucur.x), bflo(ucur.y), bfhi(ucur.y)};
; #pragma unroll
;                 for (int j = 0; j < 4; ++j) { const float y = acc[j] + dd[j] * uf[j]; o[j] = y * fsigmoid(1.5957691216057308f * (y + 0.044715f * y * y * y)); }
;                 u32x2 w; w.x = cvt_pk_bf16(o[0], o[1]); w.y = cvt_pk_bf16(o[2], o[3]);
;                 *(u32x2*)(ypre + tok * 512 + g * 16 + 4 * fq) = w;
;             }
	ds_write_b64 v146, v[64:65]
	ds_read_b128 v[192:195], v69 offset:8448
	ds_read_b128 v[204:207], v69 offset:8512
	ds_read_b128 v[212:215], v69 offset:8576
	ds_read_b128 v[216:219], v69 offset:8640
	ds_read_b128 v[156:159], v196
	ds_read_b128 v[200:203], v197
	global_load_dwordx2 v[142:143], v[60:61], off nt
	v_lshl_add_u64 v[60:61], v[60:61], 0, s[18:19]
	v_fma_f32 v70, v56, v54, v120
	v_fma_f32 v71, v56, v55, v226
	v_lshlrev_b32_e32 v76, 16, v144
	v_fma_f32 v72, v36, v55, v70
	v_fma_f32 v73, v37, v54, v71
	v_cvt_pk_bf16_f32 v74, v72, v73
	v_and_b32_e32 v77, 0xffff0000, v144
	v_fma_f32 v70, v56, v72, v121
	v_fma_f32 v71, v56, v73, v227
	v_lshlrev_b32_e32 v78, 16, v145
	v_fma_f32 v54, v36, v73, v70
	v_fma_f32 v55, v37, v72, v71
	v_cvt_pk_bf16_f32 v75, v54, v55
	v_and_b32_e32 v79, 0xffff0000, v145
	ds_write2_b32 v242, v74, v75 offset0:0 offset1:68
	s_waitcnt lgkmcnt(3)
	v_mfma_f32_16x16x32_bf16 v[220:223], v[0:3], v[192:195], 0
	v_mfma_f32_16x16x32_bf16 v[220:223], v[4:7], v[204:207], v[220:223]
	v_mfma_f32_16x16x32_bf16 v[220:223], v[8:11], v[212:215], v[220:223]
	v_mfma_f32_16x16x32_bf16 v[220:223], v[12:15], v[216:219], v[220:223]
	v_fma_f32 v70, v56, v54, v122
	v_fma_f32 v71, v56, v55, v228
	v_fma_f32 v72, v36, v55, v70
	v_fma_f32 v73, v37, v54, v71
	v_cvt_pk_bf16_f32 v74, v72, v73
	v_fma_f32 v70, v56, v72, v123
	v_fma_f32 v71, v56, v73, v229
	v_fma_f32 v54, v36, v73, v70
	v_fma_f32 v55, v37, v72, v71
	v_cvt_pk_bf16_f32 v75, v54, v55
	ds_write2_b32 v242, v74, v75 offset0:136 offset1:204
	s_waitcnt lgkmcnt(2)
	v_mfma_f32_32x32x16_bf16 v[88:103], v[156:159], v[38:41], 0
	v_mfma_f32_32x32x16_bf16 v[104:119], v[156:159], v[46:49], 0
	v_fma_f32 v70, v56, v54, v124
	v_fma_f32 v71, v56, v55, v230
	v_fma_f32 v80, v16, v76, v220
	v_fma_f32 v81, v17, v77, v221
	v_fma_f32 v72, v36, v55, v70
	v_fma_f32 v73, v37, v54, v71
	v_cvt_pk_bf16_f32 v74, v72, v73
	v_fma_f32 v82, v18, v78, v222
	v_fma_f32 v83, v19, v79, v223
	v_fma_f32 v70, v56, v72, v125
	v_fma_f32 v71, v56, v73, v231
	v_mul_f32_e32 v84, 0x3d372713, v80
	v_mul_f32_e32 v85, 0x3d372713, v81
	v_fma_f32 v54, v36, v73, v70
	v_fma_f32 v55, v37, v72, v71
	v_cvt_pk_bf16_f32 v75, v54, v55
	v_mul_f32_e32 v86, 0x3d372713, v82
	v_mul_f32_e32 v87, 0x3d372713, v83
	ds_write2_b32 v243, v74, v75 offset0:0 offset1:68
	v_mfma_f32_32x32x16_bf16 v[88:103], v[200:203], v[42:45], v[88:103]
	v_mfma_f32_32x32x16_bf16 v[104:119], v[200:203], v[50:53], v[104:119]
	v_fma_f32 v70, v56, v54, v126
	v_fma_f32 v71, v56, v55, v232
	v_mul_f32_e32 v84, v80, v84
	v_mul_f32_e32 v85, v81, v85
	v_fma_f32 v72, v36, v55, v70
	v_fma_f32 v73, v37, v54, v71
	v_cvt_pk_bf16_f32 v74, v72, v73
	v_mul_f32_e32 v86, v82, v86
	v_mul_f32_e32 v87, v83, v87
	v_fma_f32 v70, v56, v72, v127
	v_fma_f32 v71, v56, v73, v233
	v_fma_f32 v84, v80, v84, v80
	v_fma_f32 v85, v81, v85, v81
	v_fma_f32 v54, v36, v73, v70
	v_fma_f32 v55, v37, v72, v71
	v_cvt_pk_bf16_f32 v75, v54, v55
	v_fma_f32 v86, v82, v86, v82
	v_fma_f32 v87, v83, v87, v83
	ds_write2_b32 v243, v74, v75 offset0:136 offset1:204
	v_fma_f32 v70, v56, v54, v128
	v_fma_f32 v71, v56, v55, v234
	v_mul_f32_e32 v84, 0x3fcc422a, v84
	v_mul_f32_e32 v85, 0x3fcc422a, v85
	v_fma_f32 v72, v36, v55, v70
	v_fma_f32 v73, v37, v54, v71
	v_cvt_pk_bf16_f32 v74, v72, v73
	v_mul_f32_e32 v86, 0x3fcc422a, v86
	v_mul_f32_e32 v87, 0x3fcc422a, v87
	v_fma_f32 v70, v56, v72, v129
	v_fma_f32 v71, v56, v73, v235
	v_mul_f32_e32 v84, 0xbfb8aa3b, v84
	v_mul_f32_e32 v85, 0xbfb8aa3b, v85
	v_fma_f32 v54, v36, v73, v70
	v_fma_f32 v55, v37, v72, v71
	v_cvt_pk_bf16_f32 v75, v54, v55
	v_mul_f32_e32 v86, 0xbfb8aa3b, v86
	ds_write2_b32 v244, v74, v75 offset0:0 offset1:68
	v_fma_f32 v70, v56, v54, v130
	v_fma_f32 v71, v56, v55, v236
	v_mul_f32_e32 v87, 0xbfb8aa3b, v87
	v_exp_f32_e32 v84, v84
	v_fma_f32 v72, v36, v55, v70
	v_fma_f32 v73, v37, v54, v71
	v_cvt_pk_bf16_f32 v74, v72, v73
	v_exp_f32_e32 v85, v85
	v_exp_f32_e32 v86, v86
	v_fma_f32 v70, v56, v72, v131
	v_fma_f32 v71, v56, v73, v237
	v_exp_f32_e32 v87, v87
	v_add_f32_e32 v84, 1.0, v84
	v_fma_f32 v54, v36, v73, v70
	v_fma_f32 v55, v37, v72, v71
	v_cvt_pk_bf16_f32 v75, v54, v55
	v_add_f32_e32 v85, 1.0, v85
	ds_write2_b32 v244, v74, v75 offset0:136 offset1:204
	v_fma_f32 v70, v56, v54, v132
	v_fma_f32 v71, v56, v55, v238
	v_add_f32_e32 v86, 1.0, v86
	v_add_f32_e32 v87, 1.0, v87
	v_fma_f32 v72, v36, v55, v70
	v_fma_f32 v73, v37, v54, v71
	v_cvt_pk_bf16_f32 v74, v72, v73
	v_rcp_f32_e32 v84, v84
	v_rcp_f32_e32 v85, v85
	v_fma_f32 v70, v56, v72, v133
	v_fma_f32 v71, v56, v73, v239
	v_rcp_f32_e32 v86, v86
	v_rcp_f32_e32 v87, v87
	v_fma_f32 v54, v36, v73, v70
	v_fma_f32 v55, v37, v72, v71
	v_cvt_pk_bf16_f32 v75, v54, v55
	s_nop 0
	ds_write2_b32 v245, v74, v75 offset0:0 offset1:68
	v_fma_f32 v70, v56, v54, v134
	v_fma_f32 v71, v56, v55, v240
	v_mul_f32_e32 v84, v80, v84
	v_mul_f32_e32 v85, v81, v85
	v_fma_f32 v72, v36, v55, v70
	v_fma_f32 v73, v37, v54, v71
	v_cvt_pk_bf16_f32 v74, v72, v73
	v_mul_f32_e32 v86, v82, v86
	v_mul_f32_e32 v87, v83, v87
	v_fma_f32 v70, v56, v72, v135
	v_fma_f32 v71, v56, v73, v241
	v_cvt_pk_bf16_f32 v84, v84, v85
	v_fma_f32 v54, v36, v73, v70
	v_fma_f32 v55, v37, v72, v71
	v_cvt_pk_bf16_f32 v75, v54, v55
	v_cvt_pk_bf16_f32 v85, v86, v87
	ds_write2_b32 v245, v74, v75 offset0:136 offset1:204
	global_store_dwordx2 v[246:247], v[84:85], off
	s_mov_b64 s[18:19], 0x4000
	v_lshl_add_u64 v[246:247], v[246:247], 0, s[18:19]
	s_mov_b64 s[18:19], 0x8000
	s_addk_i32 s12, 0x80
	s_cmpk_eq_i32 s12, 0x400
	s_cbranch_scc0 .Lp2_loop
; #define LAS __attribute__((address_space(3)))
; __device__ __forceinline__ unsigned cvt_pk_bf16(float lo, float hi) { const f32x2 v = {lo, hi}; return __builtin_bit_cast(unsigned, __builtin_convertvector(v, bfx2_t)); }
; __device__ __forceinline__ float bflo(unsigned w) { return __uint_as_float(w << 16); }
; __device__ __forceinline__ float bfhi(unsigned w) { return __uint_as_float(w & 0xffff0000u); }
; __device__ __forceinline__ float fsigmoid(float x) { return __builtin_amdgcn_rcpf(1.0f + __builtin_amdgcn_exp2f(-1.4426950408889634f * x)); }
; template <int PASS> __device__ void ssm_pass(const Params& P, int l, LAS unsigned char* lds) {
;     ...
;                 f32x4 acc = (f32x4){0.f, 0.f, 0.f, 0.f};
; #pragma unroll
;                 for (int kt = 0; kt < 4; ++kt) { const bf16x8 sv = *(const LAS bf16x8*)(SI + fr * 272 + (32 * kt + 8 * fq) * 2);
;                     acc = __builtin_amdgcn_mfma_f32_16x16x32_bf16(cf[kt], sv, acc, 0, 0, 0); }
;                 const size_t tok = tok0 + 16 * mt + fr;
;                 float o[4];
;                 const float uf[4] = {bflo(ucur.x), bfhi(ucur.x), bflo(ucur.y), bfhi(ucur.y)};
; #pragma unroll
;                 for (int j = 0; j < 4; ++j) { const float y = acc[j] + dd[j] * uf[j]; o[j] = y * fsigmoid(1.5957691216057308f * (y + 0.044715f * y * y * y)); }
;                 u32x2 w; w.x = cvt_pk_bf16(o[0], o[1]); w.y = cvt_pk_bf16(o[2], o[3]);
;                 *(u32x2*)(ypre + tok * 512 + g * 16 + 4 * fq) = w;
	ds_read_b128 v[192:195], v69 offset:8448
	ds_read_b128 v[204:207], v69 offset:8512
	ds_read_b128 v[212:215], v69 offset:8576
	ds_read_b128 v[216:219], v69 offset:8640
	s_waitcnt lgkmcnt(0)
	v_mfma_f32_16x16x32_bf16 v[220:223], v[0:3], v[192:195], 0
	v_mfma_f32_16x16x32_bf16 v[220:223], v[4:7], v[204:207], v[220:223]
	v_mfma_f32_16x16x32_bf16 v[220:223], v[8:11], v[212:215], v[220:223]
	v_mfma_f32_16x16x32_bf16 v[220:223], v[12:15], v[216:219], v[220:223]
	s_nop 7
	s_nop 1
	v_lshlrev_b32_e32 v76, 16, v148
	v_and_b32_e32 v77, 0xffff0000, v148
	v_lshlrev_b32_e32 v78, 16, v149
	v_and_b32_e32 v79, 0xffff0000, v149
	v_fma_f32 v80, v16, v76, v220
	v_fma_f32 v81, v17, v77, v221
	v_fma_f32 v82, v18, v78, v222
	v_fma_f32 v83, v19, v79, v223
	v_mul_f32_e32 v84, 0x3d372713, v80
	v_mul_f32_e32 v85, 0x3d372713, v81
	v_mul_f32_e32 v86, 0x3d372713, v82
	v_mul_f32_e32 v87, 0x3d372713, v83
	v_mul_f32_e32 v84, v80, v84
	v_mul_f32_e32 v85, v81, v85
	v_mul_f32_e32 v86, v82, v86
	v_mul_f32_e32 v87, v83, v87
	v_fma_f32 v84, v80, v84, v80
	v_fma_f32 v85, v81, v85, v81
	v_fma_f32 v86, v82, v86, v82
	v_fma_f32 v87, v83, v87, v83
	v_mul_f32_e32 v84, 0x3fcc422a, v84
	v_mul_f32_e32 v85, 0x3fcc422a, v85
	v_mul_f32_e32 v86, 0x3fcc422a, v86
	v_mul_f32_e32 v87, 0x3fcc422a, v87
	v_mul_f32_e32 v84, 0xbfb8aa3b, v84
	v_mul_f32_e32 v85, 0xbfb8aa3b, v85
	v_mul_f32_e32 v86, 0xbfb8aa3b, v86
	v_mul_f32_e32 v87, 0xbfb8aa3b, v87
	v_exp_f32_e32 v84, v84
	v_exp_f32_e32 v85, v85
	v_exp_f32_e32 v86, v86
	v_exp_f32_e32 v87, v87
	v_add_f32_e32 v84, 1.0, v84
	v_add_f32_e32 v85, 1.0, v85
	v_add_f32_e32 v86, 1.0, v86
	v_add_f32_e32 v87, 1.0, v87
	v_rcp_f32_e32 v84, v84
	v_rcp_f32_e32 v85, v85
	v_rcp_f32_e32 v86, v86
	v_rcp_f32_e32 v87, v87
	s_nop 0
	v_mul_f32_e32 v84, v80, v84
	v_mul_f32_e32 v85, v81, v85
	v_mul_f32_e32 v86, v82, v86
	v_mul_f32_e32 v87, v83, v87
	v_cvt_pk_bf16_f32 v84, v84, v85
	v_cvt_pk_bf16_f32 v85, v86, v87
	global_store_dwordx2 v[246:247], v[84:85], off
	s_waitcnt vmcnt(0)
	s_mov_b64 s[12:13], 0x400
	s_branch .LBB0_323

; __device__ __forceinline__ float bf2f(bf16_t v) { return __uint_as_float(((unsigned)v) << 16); }
; template <int W> __device__ __forceinline__ void pool_round2(const bf16_t* zpa, bf16_t* mpa, const bf16_t* zpb, bf16_t* mpb, int t0) {
;     float a[W - 1 + 16], c[W - 1 + 16];
; #pragma unroll
;     for (int i = 0; i < W - 1 + 16; ++i) { const int t = t0 - (W - 1) + i; a[i] = (t >= 0) ? bf2f(zpa[(size_t)t * DM]) : 0.f; c[i] = (t >= 0) ? bf2f(zpb[(size_t)t * DM]) : 0.f; }
;     float sa = 0.f, sc = 0.f;
; #pragma unroll
;     for (int i = 0; i < W - 1; ++i) { sa += a[i]; sc += c[i]; }
; #pragma unroll
; __device__ void pool_phase(const Params& P) {
;     ...
;     for (int q = blockIdx.x; q < 2048; q += G) {
;         const int t0 = (q & 255) * 16, b0 = (q >> 8) * 2;
;         const bf16_t* zpa = z + (size_t)b0 * SEQ * DM + 512 + ch; bf16_t* mpa = mix + (size_t)b0 * SEQ * DM + 512 + ch;
;         const bf16_t* zpb = zpa + (size_t)SEQ * DM; bf16_t* mpb = mpa + (size_t)SEQ * DM;
;         if (gi == 0) pool_round2<2>(zpa, mpa, zpb, mpb, t0); else if (gi == 1) pool_round2<4>(zpa, mpa, zpb, mpb, t0); else if (gi == 2) pool_round2<8>(zpa, mpa, zpb, mpb, t0); else pool_round2<16>(zpa, mpa, zpb, mpb, t0);
.Lpool_w16_loop:
	s_sub_u32 s26, s18, 0x7800
	s_subb_u32 s27, s19, 0
	global_load_dword v12, v0, s[26:27] nt
	s_add_u32 s26, s26, 0x800
	s_addc_u32 s27, s27, 0
	global_load_dword v13, v0, s[26:27] nt
	s_add_u32 s26, s26, 0x800
	s_addc_u32 s27, s27, 0
	global_load_dword v14, v0, s[26:27] nt
	s_add_u32 s26, s26, 0x800
	s_addc_u32 s27, s27, 0
	global_load_dword v15, v0, s[26:27] nt
	s_add_u32 s26, s26, 0x800
	s_addc_u32 s27, s27, 0
	global_load_dword v16, v0, s[26:27] nt
	s_add_u32 s26, s26, 0x800
	s_addc_u32 s27, s27, 0
	global_load_dword v17, v0, s[26:27] nt
	s_add_u32 s26, s26, 0x800
	s_addc_u32 s27, s27, 0
	global_load_dword v18, v0, s[26:27] nt
	s_add_u32 s26, s26, 0x800
	s_addc_u32 s27, s27, 0
	global_load_dword v19, v0, s[26:27] nt
	s_add_u32 s26, s26, 0x800
	s_addc_u32 s27, s27, 0
	global_load_dword v20, v0, s[26:27] nt
	s_add_u32 s26, s26, 0x800
	s_addc_u32 s27, s27, 0
	global_load_dword v21, v0, s[26:27] nt
	s_add_u32 s26, s26, 0x800
	s_addc_u32 s27, s27, 0
	global_load_dword v22, v0, s[26:27] nt
	s_add_u32 s26, s26, 0x800
	s_addc_u32 s27, s27, 0
	global_load_dword v23, v0, s[26:27] nt
	s_add_u32 s26, s26, 0x800
	s_addc_u32 s27, s27, 0
	global_load_dword v24, v0, s[26:27] nt
	s_add_u32 s26, s26, 0x800
	s_addc_u32 s27, s27, 0
	global_load_dword v25, v0, s[26:27] nt
	s_add_u32 s26, s26, 0x800
	s_addc_u32 s27, s27, 0
	global_load_dword v26, v0, s[26:27] nt
	s_add_u32 s26, s26, 0x800
	s_addc_u32 s27, s27, 0
	global_load_dword v27, v0, s[26:27] nt
	s_add_u32 s26, s26, 0x800
	s_addc_u32 s27, s27, 0
	global_load_dword v28, v0, s[26:27] nt
	s_add_u32 s26, s26, 0x800
	s_addc_u32 s27, s27, 0
	global_load_dword v29, v0, s[26:27] nt
	s_add_u32 s26, s26, 0x800
	s_addc_u32 s27, s27, 0
	global_load_dword v30, v0, s[26:27] nt
	s_add_u32 s26, s26, 0x800
	s_addc_u32 s27, s27, 0
	global_load_dword v31, v0, s[26:27] nt
	s_add_u32 s26, s26, 0x800
	s_addc_u32 s27, s27, 0
	global_load_dword v32, v0, s[26:27] nt
	s_add_u32 s26, s26, 0x800
	s_addc_u32 s27, s27, 0
	global_load_dword v33, v0, s[26:27] nt
	s_add_u32 s26, s26, 0x800
	s_addc_u32 s27, s27, 0
	global_load_dword v34, v0, s[26:27] nt
	s_add_u32 s26, s26, 0x800
	s_addc_u32 s27, s27, 0
	global_load_dword v35, v0, s[26:27] nt
	s_add_u32 s26, s26, 0x800
	s_addc_u32 s27, s27, 0
	global_load_dword v36, v0, s[26:27] nt
	s_add_u32 s26, s26, 0x800
	s_addc_u32 s27, s27, 0
	global_load_dword v37, v0, s[26:27] nt
	s_add_u32 s26, s26, 0x800
	s_addc_u32 s27, s27, 0
	global_load_dword v38, v0, s[26:27] nt
	s_add_u32 s26, s26, 0x800
	s_addc_u32 s27, s27, 0
	global_load_dword v39, v0, s[26:27] nt
	s_add_u32 s26, s26, 0x800
	s_addc_u32 s27, s27, 0
	global_load_dword v40, v0, s[26:27] nt
	s_add_u32 s26, s26, 0x800
	s_addc_u32 s27, s27, 0
	global_load_dword v41, v0, s[26:27] nt
	s_add_u32 s26, s26, 0x800
	s_addc_u32 s27, s27, 0
	global_load_dword v42, v0, s[26:27] nt
	s_add_u32 s28, s18, 0x8000000
	s_addc_u32 s29, s19, 0
	s_waitcnt vmcnt(0)
	v_and_b32_e32 v12, s14, v12
	v_and_b32_e32 v13, s14, v13
	v_and_b32_e32 v14, s14, v14
	v_and_b32_e32 v15, s14, v15
	v_and_b32_e32 v16, s14, v16
	v_and_b32_e32 v17, s14, v17
	v_and_b32_e32 v18, s14, v18
	v_and_b32_e32 v19, s14, v19
	v_and_b32_e32 v20, s14, v20
	v_and_b32_e32 v21, s14, v21
	v_and_b32_e32 v22, s14, v22
	v_and_b32_e32 v23, s14, v23
	v_and_b32_e32 v24, s14, v24
	v_and_b32_e32 v25, s14, v25
	v_and_b32_e32 v26, s14, v26
	v_and_b32_e32 v82, 0xffff0000, v12
	v_lshlrev_b32_e32 v12, 16, v12
	v_and_b32_e32 v83, 0xffff0000, v13
	v_lshlrev_b32_e32 v13, 16, v13
	v_and_b32_e32 v84, 0xffff0000, v14
	v_lshlrev_b32_e32 v14, 16, v14
	v_and_b32_e32 v85, 0xffff0000, v15
	v_lshlrev_b32_e32 v15, 16, v15
	v_and_b32_e32 v86, 0xffff0000, v16
	v_lshlrev_b32_e32 v16, 16, v16
	v_and_b32_e32 v87, 0xffff0000, v17
	v_lshlrev_b32_e32 v17, 16, v17
	v_and_b32_e32 v88, 0xffff0000, v18
	v_lshlrev_b32_e32 v18, 16, v18
	v_and_b32_e32 v89, 0xffff0000, v19
	v_lshlrev_b32_e32 v19, 16, v19
	v_and_b32_e32 v90, 0xffff0000, v20
	v_lshlrev_b32_e32 v20, 16, v20
	v_and_b32_e32 v91, 0xffff0000, v21
	v_lshlrev_b32_e32 v21, 16, v21
	v_and_b32_e32 v92, 0xffff0000, v22
	v_lshlrev_b32_e32 v22, 16, v22
	v_and_b32_e32 v93, 0xffff0000, v23
	v_lshlrev_b32_e32 v23, 16, v23
	v_and_b32_e32 v94, 0xffff0000, v24
	v_lshlrev_b32_e32 v24, 16, v24
	v_and_b32_e32 v95, 0xffff0000, v25
	v_lshlrev_b32_e32 v25, 16, v25
	v_and_b32_e32 v96, 0xffff0000, v26
	v_lshlrev_b32_e32 v26, 16, v26
	v_and_b32_e32 v97, 0xffff0000, v27
	v_lshlrev_b32_e32 v27, 16, v27
	v_and_b32_e32 v98, 0xffff0000, v28
	v_lshlrev_b32_e32 v28, 16, v28
	v_and_b32_e32 v99, 0xffff0000, v29
	v_lshlrev_b32_e32 v29, 16, v29
	v_and_b32_e32 v100, 0xffff0000, v30
	v_lshlrev_b32_e32 v30, 16, v30
	v_and_b32_e32 v101, 0xffff0000, v31
	v_lshlrev_b32_e32 v31, 16, v31
	v_and_b32_e32 v102, 0xffff0000, v32
	v_lshlrev_b32_e32 v32, 16, v32
	v_and_b32_e32 v103, 0xffff0000, v33
	v_lshlrev_b32_e32 v33, 16, v33
	v_and_b32_e32 v104, 0xffff0000, v34
	v_lshlrev_b32_e32 v34, 16, v34
	v_and_b32_e32 v105, 0xffff0000, v35
	v_lshlrev_b32_e32 v35, 16, v35
	v_and_b32_e32 v106, 0xffff0000, v36
	v_lshlrev_b32_e32 v36, 16, v36
	v_and_b32_e32 v107, 0xffff0000, v37
	v_lshlrev_b32_e32 v37, 16, v37
	v_and_b32_e32 v108, 0xffff0000, v38
	v_lshlrev_b32_e32 v38, 16, v38
	v_and_b32_e32 v109, 0xffff0000, v39
	v_lshlrev_b32_e32 v39, 16, v39
	v_and_b32_e32 v110, 0xffff0000, v40
	v_lshlrev_b32_e32 v40, 16, v40
	v_and_b32_e32 v111, 0xffff0000, v41
	v_lshlrev_b32_e32 v41, 16, v41
	v_and_b32_e32 v112, 0xffff0000, v42
	v_lshlrev_b32_e32 v42, 16, v42
	v_add_f32_e32 v4, 0, v12
	v_add_f32_e32 v5, 0, v82
	v_add_f32_e32 v4, v4, v13
	v_add_f32_e32 v5, v5, v83
	v_add_f32_e32 v4, v4, v14
	v_add_f32_e32 v5, v5, v84
; __device__ __forceinline__ bf16_t f2bf(float f) { unsigned u = __float_as_uint(f); u += 0x7FFFu + ((u >> 16) & 1u); return (bf16_t)(u >> 16); }
; template <int W> __device__ __forceinline__ void pool_round2(const bf16_t* zpa, bf16_t* mpa, const bf16_t* zpb, bf16_t* mpb, int t0) {
;     ...
;     for (int j = 0; j < 16; ++j) {
;         const int t = t0 + j; const float va = a[W - 1 + j], vc = c[W - 1 + j]; sa += va; sc += vc;
;         const float inv = 1.0f / (float)((t + 1 < W) ? t + 1 : W);
;         mpa[(size_t)t * DM] = f2bf(sa * inv - va); mpb[(size_t)t * DM] = f2bf(sc * inv - vc);
;         sa -= a[j]; sc -= c[j];
;     }
	v_add_f32_e32 v4, v4, v15
	v_add_f32_e32 v5, v5, v85
	v_add_f32_e32 v4, v4, v16
	v_add_f32_e32 v5, v5, v86
	v_add_f32_e32 v4, v4, v17
	v_add_f32_e32 v5, v5, v87
	v_add_f32_e32 v4, v4, v18
	v_add_f32_e32 v5, v5, v88
	v_add_f32_e32 v4, v4, v19
	v_add_f32_e32 v5, v5, v89
	v_add_f32_e32 v4, v4, v20
	v_add_f32_e32 v5, v5, v90
	v_add_f32_e32 v4, v4, v21
	v_add_f32_e32 v5, v5, v91
	v_add_f32_e32 v4, v4, v22
	v_add_f32_e32 v5, v5, v92
	v_add_f32_e32 v4, v4, v23
	v_add_f32_e32 v5, v5, v93
	v_add_f32_e32 v4, v4, v24
	v_add_f32_e32 v5, v5, v94
	v_add_f32_e32 v4, v4, v25
	v_add_f32_e32 v5, v5, v95
	v_add_f32_e32 v4, v4, v26
	v_add_f32_e32 v5, v5, v96
	s_cmp_eq_u32 s12, 0
	s_cselect_b32 s32, 0x3f800000, s56
	v_add_f32_e32 v4, v4, v27
	v_add_f32_e32 v5, v5, v97
	v_fma_f32 v6, s32, v4, -v27
	v_fma_f32 v7, s32, v5, -v97
	v_sub_f32_e32 v4, v4, v12
	v_sub_f32_e32 v5, v5, v82
	v_cvt_pk_bf16_f32 v113, v6, v7
	global_store_dword v0, v113, s[28:29]
	s_add_u32 s28, s28, 0x800
	s_addc_u32 s29, s29, 0
	s_cmp_eq_u32 s12, 0
	s_cselect_b32 s32, 0x3f000000, s56
	v_add_f32_e32 v4, v4, v28
	v_add_f32_e32 v5, v5, v98
	v_fma_f32 v6, s32, v4, -v28
	v_fma_f32 v7, s32, v5, -v98
	v_sub_f32_e32 v4, v4, v13
	v_sub_f32_e32 v5, v5, v83
	v_cvt_pk_bf16_f32 v114, v6, v7
	global_store_dword v0, v114, s[28:29]
	s_add_u32 s28, s28, 0x800
	s_addc_u32 s29, s29, 0
	s_cmp_eq_u32 s12, 0
	s_cselect_b32 s32, 0x3eaaaaab, s56
	v_add_f32_e32 v4, v4, v29
	v_add_f32_e32 v5, v5, v99
	v_fma_f32 v6, s32, v4, -v29
	v_fma_f32 v7, s32, v5, -v99
	v_sub_f32_e32 v4, v4, v14
	v_sub_f32_e32 v5, v5, v84
	v_cvt_pk_bf16_f32 v115, v6, v7
	global_store_dword v0, v115, s[28:29]
	s_add_u32 s28, s28, 0x800
	s_addc_u32 s29, s29, 0
	s_cmp_eq_u32 s12, 0
	s_cselect_b32 s32, 0x3e800000, s56
	v_add_f32_e32 v4, v4, v30
	v_add_f32_e32 v5, v5, v100
	v_fma_f32 v6, s32, v4, -v30
	v_fma_f32 v7, s32, v5, -v100
	v_sub_f32_e32 v4, v4, v15
	v_sub_f32_e32 v5, v5, v85
	v_cvt_pk_bf16_f32 v116, v6, v7
	global_store_dword v0, v116, s[28:29]
	s_add_u32 s28, s28, 0x800
	s_addc_u32 s29, s29, 0
	s_cmp_eq_u32 s12, 0
	s_cselect_b32 s32, 0x3e4ccccd, s56
	v_add_f32_e32 v4, v4, v31
	v_add_f32_e32 v5, v5, v101
	v_fma_f32 v6, s32, v4, -v31
	v_fma_f32 v7, s32, v5, -v101
	v_sub_f32_e32 v4, v4, v16
	v_sub_f32_e32 v5, v5, v86
	v_cvt_pk_bf16_f32 v117, v6, v7
	global_store_dword v0, v117, s[28:29]
	s_add_u32 s28, s28, 0x800
	s_addc_u32 s29, s29, 0
	s_cmp_eq_u32 s12, 0
	s_cselect_b32 s32, 0x3e2aaaab, s56
	v_add_f32_e32 v4, v4, v32
	v_add_f32_e32 v5, v5, v102
	v_fma_f32 v6, s32, v4, -v32
	v_fma_f32 v7, s32, v5, -v102
	v_sub_f32_e32 v4, v4, v17
	v_sub_f32_e32 v5, v5, v87
	v_cvt_pk_bf16_f32 v118, v6, v7
	global_store_dword v0, v118, s[28:29]
	s_add_u32 s28, s28, 0x800
	s_addc_u32 s29, s29, 0
	s_cmp_eq_u32 s12, 0
	s_cselect_b32 s32, 0x3e124925, s56
	v_add_f32_e32 v4, v4, v33
	v_add_f32_e32 v5, v5, v103
	v_fma_f32 v6, s32, v4, -v33
	v_fma_f32 v7, s32, v5, -v103
	v_sub_f32_e32 v4, v4, v18
	v_sub_f32_e32 v5, v5, v88
	v_cvt_pk_bf16_f32 v119, v6, v7
	global_store_dword v0, v119, s[28:29]
	s_add_u32 s28, s28, 0x800
	s_addc_u32 s29, s29, 0
	s_cmp_eq_u32 s12, 0
	s_cselect_b32 s32, 0x3e000000, s56
	v_add_f32_e32 v4, v4, v34
	v_add_f32_e32 v5, v5, v104
	v_fma_f32 v6, s32, v4, -v34
	v_fma_f32 v7, s32, v5, -v104
	v_sub_f32_e32 v4, v4, v19
	v_sub_f32_e32 v5, v5, v89
	v_cvt_pk_bf16_f32 v120, v6, v7
	global_store_dword v0, v120, s[28:29]
	s_add_u32 s28, s28, 0x800
	s_addc_u32 s29, s29, 0
	s_cmp_eq_u32 s12, 0
	s_cselect_b32 s32, 0x3de38e39, s56
	v_add_f32_e32 v4, v4, v35
	v_add_f32_e32 v5, v5, v105
	v_fma_f32 v6, s32, v4, -v35
	v_fma_f32 v7, s32, v5, -v105
	v_sub_f32_e32 v4, v4, v20
	v_sub_f32_e32 v5, v5, v90
	v_cvt_pk_bf16_f32 v121, v6, v7
	global_store_dword v0, v121, s[28:29]
	s_add_u32 s28, s28, 0x800
	s_addc_u32 s29, s29, 0
	s_cmp_eq_u32 s12, 0
	s_cselect_b32 s32, 0x3dcccccd, s56
	v_add_f32_e32 v4, v4, v36
	v_add_f32_e32 v5, v5, v106
	v_fma_f32 v6, s32, v4, -v36
	v_fma_f32 v7, s32, v5, -v106
	v_sub_f32_e32 v4, v4, v21
	v_sub_f32_e32 v5, v5, v91
	v_cvt_pk_bf16_f32 v122, v6, v7
	global_store_dword v0, v122, s[28:29]
	s_add_u32 s28, s28, 0x800
	s_addc_u32 s29, s29, 0
	s_cmp_eq_u32 s12, 0
	s_cselect_b32 s32, 0x3dba2e8c, s56
	v_add_f32_e32 v4, v4, v37
	v_add_f32_e32 v5, v5, v107
	v_fma_f32 v6, s32, v4, -v37
	v_fma_f32 v7, s32, v5, -v107
	v_sub_f32_e32 v4, v4, v22
	v_sub_f32_e32 v5, v5, v92
	v_cvt_pk_bf16_f32 v123, v6, v7
	global_store_dword v0, v123, s[28:29]
	s_add_u32 s28, s28, 0x800
	s_addc_u32 s29, s29, 0
	s_cmp_eq_u32 s12, 0
	s_cselect_b32 s32, 0x3daaaaab, s56
	v_add_f32_e32 v4, v4, v38
	v_add_f32_e32 v5, v5, v108
	v_fma_f32 v6, s32, v4, -v38
	v_fma_f32 v7, s32, v5, -v108
	v_sub_f32_e32 v4, v4, v23
	v_sub_f32_e32 v5, v5, v93
	v_cvt_pk_bf16_f32 v124, v6, v7
	global_store_dword v0, v124, s[28:29]
	s_add_u32 s28, s28, 0x800
	s_addc_u32 s29, s29, 0
	s_cmp_eq_u32 s12, 0
	s_cselect_b32 s32, 0x3d9d89d9, s56
	v_add_f32_e32 v4, v4, v39
	v_add_f32_e32 v5, v5, v109
	v_fma_f32 v6, s32, v4, -v39
	v_fma_f32 v7, s32, v5, -v109
	v_sub_f32_e32 v4, v4, v24
	v_sub_f32_e32 v5, v5, v94
	v_cvt_pk_bf16_f32 v125, v6, v7
	global_store_dword v0, v125, s[28:29]
	s_add_u32 s28, s28, 0x800
	s_addc_u32 s29, s29, 0
	s_cmp_eq_u32 s12, 0
	s_cselect_b32 s32, 0x3d924925, s56
	v_add_f32_e32 v4, v4, v40
	v_add_f32_e32 v5, v5, v110
	v_fma_f32 v6, s32, v4, -v40
	v_fma_f32 v7, s32, v5, -v110
	v_sub_f32_e32 v4, v4, v25
	v_sub_f32_e32 v5, v5, v95
	v_cvt_pk_bf16_f32 v126, v6, v7
	global_store_dword v0, v126, s[28:29]
	s_add_u32 s28, s28, 0x800
	s_addc_u32 s29, s29, 0
	s_cmp_eq_u32 s12, 0
	s_cselect_b32 s32, 0x3d888889, s56
	v_add_f32_e32 v4, v4, v41
	v_add_f32_e32 v5, v5, v111
	v_fma_f32 v6, s32, v4, -v41
	v_fma_f32 v7, s32, v5, -v111
	v_sub_f32_e32 v4, v4, v26
	v_sub_f32_e32 v5, v5, v96
	v_cvt_pk_bf16_f32 v127, v6, v7
	global_store_dword v0, v127, s[28:29]
	s_add_u32 s28, s28, 0x800
	s_addc_u32 s29, s29, 0
	v_add_f32_e32 v4, v4, v42
	v_add_f32_e32 v5, v5, v112
	v_fma_f32 v6, s56, v4, -v42
	v_fma_f32 v7, s56, v5, -v112
	v_sub_f32_e32 v4, v4, v27
	v_sub_f32_e32 v5, v5, v97
	v_cvt_pk_bf16_f32 v128, v6, v7
	global_store_dword v0, v128, s[28:29]
	s_add_u32 s18, s18, 0x1000000
	s_addc_u32 s19, s19, 0
	s_sub_u32 s57, s57, 1
	s_cmp_lg_u32 s57, 0
	s_cbranch_scc1 .Lpool_w16_loop
	s_branch .LBB0_464

; __device__ __forceinline__ bf16_t f2bf(float f) { unsigned u = __float_as_uint(f); u += 0x7FFFu + ((u >> 16) & 1u); return (bf16_t)(u >> 16); }
; __device__ __forceinline__ float bf2f(bf16_t v) { return __uint_as_float(((unsigned)v) << 16); }
; template <int W> __device__ __forceinline__ void pool_round2(const bf16_t* zpa, bf16_t* mpa, const bf16_t* zpb, bf16_t* mpb, int t0) {
;     float a[W - 1 + 16], c[W - 1 + 16];
; #pragma unroll
;     for (int i = 0; i < W - 1 + 16; ++i) { const int t = t0 - (W - 1) + i; a[i] = (t >= 0) ? bf2f(zpa[(size_t)t * DM]) : 0.f; c[i] = (t >= 0) ? bf2f(zpb[(size_t)t * DM]) : 0.f; }
;     float sa = 0.f, sc = 0.f;
; #pragma unroll
;     for (int i = 0; i < W - 1; ++i) { sa += a[i]; sc += c[i]; }
; #pragma unroll
;     for (int j = 0; j < 16; ++j) {
;         const int t = t0 + j; const float va = a[W - 1 + j], vc = c[W - 1 + j]; sa += va; sc += vc;
;         const float inv = 1.0f / (float)((t + 1 < W) ? t + 1 : W);
;         mpa[(size_t)t * DM] = f2bf(sa * inv - va); mpb[(size_t)t * DM] = f2bf(sc * inv - vc);
;         sa -= a[j]; sc -= c[j];
;     }
.Lpool_w8_loop:
	s_sub_u32 s26, s18, 0x3800
	s_subb_u32 s27, s19, 0
	global_load_dword v12, v0, s[26:27] nt
	s_add_u32 s26, s26, 0x800
	s_addc_u32 s27, s27, 0
	global_load_dword v13, v0, s[26:27] nt
	s_add_u32 s26, s26, 0x800
	s_addc_u32 s27, s27, 0
	global_load_dword v14, v0, s[26:27] nt
	s_add_u32 s26, s26, 0x800
	s_addc_u32 s27, s27, 0
	global_load_dword v15, v0, s[26:27] nt
	s_add_u32 s26, s26, 0x800
	s_addc_u32 s27, s27, 0
	global_load_dword v16, v0, s[26:27] nt
	s_add_u32 s26, s26, 0x800
	s_addc_u32 s27, s27, 0
	global_load_dword v17, v0, s[26:27] nt
	s_add_u32 s26, s26, 0x800
	s_addc_u32 s27, s27, 0
	global_load_dword v18, v0, s[26:27] nt
	s_add_u32 s26, s26, 0x800
	s_addc_u32 s27, s27, 0
	global_load_dword v19, v0, s[26:27] nt
	s_add_u32 s26, s26, 0x800
	s_addc_u32 s27, s27, 0
	global_load_dword v20, v0, s[26:27] nt
	s_add_u32 s26, s26, 0x800
	s_addc_u32 s27, s27, 0
	global_load_dword v21, v0, s[26:27] nt
	s_add_u32 s26, s26, 0x800
	s_addc_u32 s27, s27, 0
	global_load_dword v22, v0, s[26:27] nt
	s_add_u32 s26, s26, 0x800
	s_addc_u32 s27, s27, 0
	global_load_dword v23, v0, s[26:27] nt
	s_add_u32 s26, s26, 0x800
	s_addc_u32 s27, s27, 0
	global_load_dword v24, v0, s[26:27] nt
	s_add_u32 s26, s26, 0x800
	s_addc_u32 s27, s27, 0
	global_load_dword v25, v0, s[26:27] nt
	s_add_u32 s26, s26, 0x800
	s_addc_u32 s27, s27, 0
	global_load_dword v26, v0, s[26:27] nt
	s_add_u32 s26, s26, 0x800
	s_addc_u32 s27, s27, 0
	global_load_dword v27, v0, s[26:27] nt
	s_add_u32 s26, s26, 0x800
	s_addc_u32 s27, s27, 0
	global_load_dword v28, v0, s[26:27] nt
	s_add_u32 s26, s26, 0x800
	s_addc_u32 s27, s27, 0
	global_load_dword v29, v0, s[26:27] nt
	s_add_u32 s26, s26, 0x800
	s_addc_u32 s27, s27, 0
	global_load_dword v30, v0, s[26:27] nt
	s_add_u32 s26, s26, 0x800
	s_addc_u32 s27, s27, 0
	global_load_dword v31, v0, s[26:27] nt
	s_add_u32 s26, s26, 0x800
	s_addc_u32 s27, s27, 0
	global_load_dword v32, v0, s[26:27] nt
	s_add_u32 s26, s26, 0x800
	s_addc_u32 s27, s27, 0
	global_load_dword v33, v0, s[26:27] nt
	s_add_u32 s26, s26, 0x800
	s_addc_u32 s27, s27, 0
	global_load_dword v34, v0, s[26:27] nt
	s_add_u32 s28, s18, 0x8000000
	s_addc_u32 s29, s19, 0
	s_waitcnt vmcnt(0)
	v_and_b32_e32 v12, s14, v12
	v_and_b32_e32 v13, s14, v13
	v_and_b32_e32 v14, s14, v14
	v_and_b32_e32 v15, s14, v15
	v_and_b32_e32 v16, s14, v16
	v_and_b32_e32 v17, s14, v17
	v_and_b32_e32 v18, s14, v18
	v_and_b32_e32 v82, 0xffff0000, v12
	v_lshlrev_b32_e32 v12, 16, v12
	v_and_b32_e32 v83, 0xffff0000, v13
	v_lshlrev_b32_e32 v13, 16, v13
	v_and_b32_e32 v84, 0xffff0000, v14
	v_lshlrev_b32_e32 v14, 16, v14
	v_and_b32_e32 v85, 0xffff0000, v15
	v_lshlrev_b32_e32 v15, 16, v15
	v_and_b32_e32 v86, 0xffff0000, v16
	v_lshlrev_b32_e32 v16, 16, v16
	v_and_b32_e32 v87, 0xffff0000, v17
	v_lshlrev_b32_e32 v17, 16, v17
	v_and_b32_e32 v88, 0xffff0000, v18
	v_lshlrev_b32_e32 v18, 16, v18
	v_and_b32_e32 v89, 0xffff0000, v19
	v_lshlrev_b32_e32 v19, 16, v19
	v_and_b32_e32 v90, 0xffff0000, v20
	v_lshlrev_b32_e32 v20, 16, v20
	v_and_b32_e32 v91, 0xffff0000, v21
	v_lshlrev_b32_e32 v21, 16, v21
	v_and_b32_e32 v92, 0xffff0000, v22
	v_lshlrev_b32_e32 v22, 16, v22
	v_and_b32_e32 v93, 0xffff0000, v23
	v_lshlrev_b32_e32 v23, 16, v23
	v_and_b32_e32 v94, 0xffff0000, v24
	v_lshlrev_b32_e32 v24, 16, v24
	v_and_b32_e32 v95, 0xffff0000, v25
	v_lshlrev_b32_e32 v25, 16, v25
	v_and_b32_e32 v96, 0xffff0000, v26
	v_lshlrev_b32_e32 v26, 16, v26
	v_and_b32_e32 v97, 0xffff0000, v27
	v_lshlrev_b32_e32 v27, 16, v27
	v_and_b32_e32 v98, 0xffff0000, v28
	v_lshlrev_b32_e32 v28, 16, v28
	v_and_b32_e32 v99, 0xffff0000, v29
	v_lshlrev_b32_e32 v29, 16, v29
	v_and_b32_e32 v100, 0xffff0000, v30
	v_lshlrev_b32_e32 v30, 16, v30
	v_and_b32_e32 v101, 0xffff0000, v31
	v_lshlrev_b32_e32 v31, 16, v31
	v_and_b32_e32 v102, 0xffff0000, v32
	v_lshlrev_b32_e32 v32, 16, v32
	v_and_b32_e32 v103, 0xffff0000, v33
	v_lshlrev_b32_e32 v33, 16, v33
	v_and_b32_e32 v104, 0xffff0000, v34
	v_lshlrev_b32_e32 v34, 16, v34
	v_add_f32_e32 v4, 0, v12
	v_add_f32_e32 v5, 0, v82
	v_add_f32_e32 v4, v4, v13
	v_add_f32_e32 v5, v5, v83
	v_add_f32_e32 v4, v4, v14
	v_add_f32_e32 v5, v5, v84
	v_add_f32_e32 v4, v4, v15
	v_add_f32_e32 v5, v5, v85
	v_add_f32_e32 v4, v4, v16
	v_add_f32_e32 v5, v5, v86
	v_add_f32_e32 v4, v4, v17
	v_add_f32_e32 v5, v5, v87
	v_add_f32_e32 v4, v4, v18
	v_add_f32_e32 v5, v5, v88
	s_cmp_eq_u32 s12, 0
	s_cselect_b32 s32, 0x3f800000, s56
	v_add_f32_e32 v4, v4, v19
	v_add_f32_e32 v5, v5, v89
	v_fma_f32 v6, s32, v4, -v19
	v_fma_f32 v7, s32, v5, -v89
	v_sub_f32_e32 v4, v4, v12
	v_sub_f32_e32 v5, v5, v82
	v_cvt_pk_bf16_f32 v113, v6, v7
	global_store_dword v0, v113, s[28:29]
	s_add_u32 s28, s28, 0x800
	s_addc_u32 s29, s29, 0
	s_cmp_eq_u32 s12, 0
	s_cselect_b32 s32, 0x3f000000, s56
; __device__ __forceinline__ bf16_t f2bf(float f) { unsigned u = __float_as_uint(f); u += 0x7FFFu + ((u >> 16) & 1u); return (bf16_t)(u >> 16); }
; template <int W> __device__ __forceinline__ void pool_round2(const bf16_t* zpa, bf16_t* mpa, const bf16_t* zpb, bf16_t* mpb, int t0) {
;     ...
;     for (int j = 0; j < 16; ++j) {
;         const int t = t0 + j; const float va = a[W - 1 + j], vc = c[W - 1 + j]; sa += va; sc += vc;
;         const float inv = 1.0f / (float)((t + 1 < W) ? t + 1 : W);
;         mpa[(size_t)t * DM] = f2bf(sa * inv - va); mpb[(size_t)t * DM] = f2bf(sc * inv - vc);
;         sa -= a[j]; sc -= c[j];
;     }
	v_add_f32_e32 v4, v4, v20
	v_add_f32_e32 v5, v5, v90
	v_fma_f32 v6, s32, v4, -v20
	v_fma_f32 v7, s32, v5, -v90
	v_sub_f32_e32 v4, v4, v13
	v_sub_f32_e32 v5, v5, v83
	v_cvt_pk_bf16_f32 v114, v6, v7
	global_store_dword v0, v114, s[28:29]
	s_add_u32 s28, s28, 0x800
	s_addc_u32 s29, s29, 0
	s_cmp_eq_u32 s12, 0
	s_cselect_b32 s32, 0x3eaaaaab, s56
	v_add_f32_e32 v4, v4, v21
	v_add_f32_e32 v5, v5, v91
	v_fma_f32 v6, s32, v4, -v21
	v_fma_f32 v7, s32, v5, -v91
	v_sub_f32_e32 v4, v4, v14
	v_sub_f32_e32 v5, v5, v84
	v_cvt_pk_bf16_f32 v115, v6, v7
	global_store_dword v0, v115, s[28:29]
	s_add_u32 s28, s28, 0x800
	s_addc_u32 s29, s29, 0
	s_cmp_eq_u32 s12, 0
	s_cselect_b32 s32, 0x3e800000, s56
	v_add_f32_e32 v4, v4, v22
	v_add_f32_e32 v5, v5, v92
	v_fma_f32 v6, s32, v4, -v22
	v_fma_f32 v7, s32, v5, -v92
	v_sub_f32_e32 v4, v4, v15
	v_sub_f32_e32 v5, v5, v85
	v_cvt_pk_bf16_f32 v116, v6, v7
	global_store_dword v0, v116, s[28:29]
	s_add_u32 s28, s28, 0x800
	s_addc_u32 s29, s29, 0
	s_cmp_eq_u32 s12, 0
	s_cselect_b32 s32, 0x3e4ccccd, s56
	v_add_f32_e32 v4, v4, v23
	v_add_f32_e32 v5, v5, v93
	v_fma_f32 v6, s32, v4, -v23
	v_fma_f32 v7, s32, v5, -v93
	v_sub_f32_e32 v4, v4, v16
	v_sub_f32_e32 v5, v5, v86
	v_cvt_pk_bf16_f32 v117, v6, v7
	global_store_dword v0, v117, s[28:29]
	s_add_u32 s28, s28, 0x800
	s_addc_u32 s29, s29, 0
	s_cmp_eq_u32 s12, 0
	s_cselect_b32 s32, 0x3e2aaaab, s56
	v_add_f32_e32 v4, v4, v24
	v_add_f32_e32 v5, v5, v94
	v_fma_f32 v6, s32, v4, -v24
	v_fma_f32 v7, s32, v5, -v94
	v_sub_f32_e32 v4, v4, v17
	v_sub_f32_e32 v5, v5, v87
	v_cvt_pk_bf16_f32 v118, v6, v7
	global_store_dword v0, v118, s[28:29]
	s_add_u32 s28, s28, 0x800
	s_addc_u32 s29, s29, 0
	s_cmp_eq_u32 s12, 0
	s_cselect_b32 s32, 0x3e124925, s56
	v_add_f32_e32 v4, v4, v25
	v_add_f32_e32 v5, v5, v95
	v_fma_f32 v6, s32, v4, -v25
	v_fma_f32 v7, s32, v5, -v95
	v_sub_f32_e32 v4, v4, v18
	v_sub_f32_e32 v5, v5, v88
	v_cvt_pk_bf16_f32 v119, v6, v7
	global_store_dword v0, v119, s[28:29]
	s_add_u32 s28, s28, 0x800
	s_addc_u32 s29, s29, 0
	v_add_f32_e32 v4, v4, v26
	v_add_f32_e32 v5, v5, v96
	v_fma_f32 v6, s56, v4, -v26
	v_fma_f32 v7, s56, v5, -v96
	v_sub_f32_e32 v4, v4, v19
	v_sub_f32_e32 v5, v5, v89
	v_cvt_pk_bf16_f32 v120, v6, v7
	global_store_dword v0, v120, s[28:29]
	s_add_u32 s28, s28, 0x800
	s_addc_u32 s29, s29, 0
	v_add_f32_e32 v4, v4, v27
	v_add_f32_e32 v5, v5, v97
	v_fma_f32 v6, s56, v4, -v27
	v_fma_f32 v7, s56, v5, -v97
	v_sub_f32_e32 v4, v4, v20
	v_sub_f32_e32 v5, v5, v90
	v_cvt_pk_bf16_f32 v121, v6, v7
	global_store_dword v0, v121, s[28:29]
	s_add_u32 s28, s28, 0x800
	s_addc_u32 s29, s29, 0
	v_add_f32_e32 v4, v4, v28
	v_add_f32_e32 v5, v5, v98
	v_fma_f32 v6, s56, v4, -v28
	v_fma_f32 v7, s56, v5, -v98
	v_sub_f32_e32 v4, v4, v21
	v_sub_f32_e32 v5, v5, v91
	v_cvt_pk_bf16_f32 v122, v6, v7
	global_store_dword v0, v122, s[28:29]
	s_add_u32 s28, s28, 0x800
	s_addc_u32 s29, s29, 0
	v_add_f32_e32 v4, v4, v29
	v_add_f32_e32 v5, v5, v99
	v_fma_f32 v6, s56, v4, -v29
	v_fma_f32 v7, s56, v5, -v99
	v_sub_f32_e32 v4, v4, v22
	v_sub_f32_e32 v5, v5, v92
	v_cvt_pk_bf16_f32 v123, v6, v7
	global_store_dword v0, v123, s[28:29]
	s_add_u32 s28, s28, 0x800
	s_addc_u32 s29, s29, 0
	v_add_f32_e32 v4, v4, v30
	v_add_f32_e32 v5, v5, v100
	v_fma_f32 v6, s56, v4, -v30
	v_fma_f32 v7, s56, v5, -v100
	v_sub_f32_e32 v4, v4, v23
	v_sub_f32_e32 v5, v5, v93
	v_cvt_pk_bf16_f32 v124, v6, v7
	global_store_dword v0, v124, s[28:29]
	s_add_u32 s28, s28, 0x800
	s_addc_u32 s29, s29, 0
	v_add_f32_e32 v4, v4, v31
	v_add_f32_e32 v5, v5, v101
	v_fma_f32 v6, s56, v4, -v31
	v_fma_f32 v7, s56, v5, -v101
	v_sub_f32_e32 v4, v4, v24
	v_sub_f32_e32 v5, v5, v94
	v_cvt_pk_bf16_f32 v125, v6, v7
	global_store_dword v0, v125, s[28:29]
	s_add_u32 s28, s28, 0x800
	s_addc_u32 s29, s29, 0
	v_add_f32_e32 v4, v4, v32
	v_add_f32_e32 v5, v5, v102
	v_fma_f32 v6, s56, v4, -v32
	v_fma_f32 v7, s56, v5, -v102
	v_sub_f32_e32 v4, v4, v25
	v_sub_f32_e32 v5, v5, v95
	v_cvt_pk_bf16_f32 v126, v6, v7
	global_store_dword v0, v126, s[28:29]
	s_add_u32 s28, s28, 0x800
	s_addc_u32 s29, s29, 0
	v_add_f32_e32 v4, v4, v33
	v_add_f32_e32 v5, v5, v103
	v_fma_f32 v6, s56, v4, -v33
	v_fma_f32 v7, s56, v5, -v103
	v_sub_f32_e32 v4, v4, v26
	v_sub_f32_e32 v5, v5, v96
	v_cvt_pk_bf16_f32 v127, v6, v7
	global_store_dword v0, v127, s[28:29]
	s_add_u32 s28, s28, 0x800
	s_addc_u32 s29, s29, 0
	v_add_f32_e32 v4, v4, v34
	v_add_f32_e32 v5, v5, v104
	v_fma_f32 v6, s56, v4, -v34
	v_fma_f32 v7, s56, v5, -v104
	v_sub_f32_e32 v4, v4, v27
	v_sub_f32_e32 v5, v5, v97
	v_cvt_pk_bf16_f32 v128, v6, v7
	global_store_dword v0, v128, s[28:29]
	s_add_u32 s18, s18, 0x1000000
	s_addc_u32 s19, s19, 0
	s_sub_u32 s57, s57, 1
	s_cmp_lg_u32 s57, 0
	s_cbranch_scc1 .Lpool_w8_loop
	s_branch .LBB0_464

; __device__ __forceinline__ float bf2f(bf16_t v) { return __uint_as_float(((unsigned)v) << 16); }
; template <int W> __device__ __forceinline__ void pool_round2(const bf16_t* zpa, bf16_t* mpa, const bf16_t* zpb, bf16_t* mpb, int t0) {
;     float a[W - 1 + 16], c[W - 1 + 16];
; #pragma unroll
;     for (int i = 0; i < W - 1 + 16; ++i) { const int t = t0 - (W - 1) + i; a[i] = (t >= 0) ? bf2f(zpa[(size_t)t * DM]) : 0.f; c[i] = (t >= 0) ? bf2f(zpb[(size_t)t * DM]) : 0.f; }
.Lpool_w4_loop:
	s_sub_u32 s26, s18, 0x1800
	s_subb_u32 s27, s19, 0
	global_load_dword v12, v0, s[26:27] nt
	s_add_u32 s26, s26, 0x800
	s_addc_u32 s27, s27, 0
	global_load_dword v13, v0, s[26:27] nt
	s_add_u32 s26, s26, 0x800
	s_addc_u32 s27, s27, 0
	global_load_dword v14, v0, s[26:27] nt
	s_add_u32 s26, s26, 0x800
	s_addc_u32 s27, s27, 0
	global_load_dword v15, v0, s[26:27] nt
	s_add_u32 s26, s26, 0x800
	s_addc_u32 s27, s27, 0
	global_load_dword v16, v0, s[26:27] nt
	s_add_u32 s26, s26, 0x800
	s_addc_u32 s27, s27, 0
	global_load_dword v17, v0, s[26:27] nt
	s_add_u32 s26, s26, 0x800
	s_addc_u32 s27, s27, 0
	global_load_dword v18, v0, s[26:27] nt
	s_add_u32 s26, s26, 0x800
	s_addc_u32 s27, s27, 0
	global_load_dword v19, v0, s[26:27] nt
	s_add_u32 s26, s26, 0x800
	s_addc_u32 s27, s27, 0
	global_load_dword v20, v0, s[26:27] nt
	s_add_u32 s26, s26, 0x800
	s_addc_u32 s27, s27, 0
	global_load_dword v21, v0, s[26:27] nt
	s_add_u32 s26, s26, 0x800
	s_addc_u32 s27, s27, 0
	global_load_dword v22, v0, s[26:27] nt
	s_add_u32 s26, s26, 0x800
	s_addc_u32 s27, s27, 0
	global_load_dword v23, v0, s[26:27] nt
	s_add_u32 s26, s26, 0x800
	s_addc_u32 s27, s27, 0
	global_load_dword v24, v0, s[26:27] nt
	s_add_u32 s26, s26, 0x800
	s_addc_u32 s27, s27, 0
	global_load_dword v25, v0, s[26:27] nt
	s_add_u32 s26, s26, 0x800
	s_addc_u32 s27, s27, 0
	global_load_dword v26, v0, s[26:27] nt
	s_add_u32 s26, s26, 0x800
	s_addc_u32 s27, s27, 0
	global_load_dword v27, v0, s[26:27] nt
	s_add_u32 s26, s26, 0x800
	s_addc_u32 s27, s27, 0
	global_load_dword v28, v0, s[26:27] nt
	s_add_u32 s26, s26, 0x800
	s_addc_u32 s27, s27, 0
	global_load_dword v29, v0, s[26:27] nt
	s_add_u32 s26, s26, 0x800
	s_addc_u32 s27, s27, 0
	global_load_dword v30, v0, s[26:27] nt
	s_add_u32 s28, s18, 0x8000000
	s_addc_u32 s29, s19, 0
	s_waitcnt vmcnt(0)
; __device__ __forceinline__ bf16_t f2bf(float f) { unsigned u = __float_as_uint(f); u += 0x7FFFu + ((u >> 16) & 1u); return (bf16_t)(u >> 16); }
; template <int W> __device__ __forceinline__ void pool_round2(const bf16_t* zpa, bf16_t* mpa, const bf16_t* zpb, bf16_t* mpb, int t0) {
;     ...
;     float sa = 0.f, sc = 0.f;
; #pragma unroll
;     for (int i = 0; i < W - 1; ++i) { sa += a[i]; sc += c[i]; }
; #pragma unroll
;     for (int j = 0; j < 16; ++j) {
;         const int t = t0 + j; const float va = a[W - 1 + j], vc = c[W - 1 + j]; sa += va; sc += vc;
;         const float inv = 1.0f / (float)((t + 1 < W) ? t + 1 : W);
;         mpa[(size_t)t * DM] = f2bf(sa * inv - va); mpb[(size_t)t * DM] = f2bf(sc * inv - vc);
;         sa -= a[j]; sc -= c[j];
;     }
	v_and_b32_e32 v12, s14, v12
	v_and_b32_e32 v13, s14, v13
	v_and_b32_e32 v14, s14, v14
	v_and_b32_e32 v82, 0xffff0000, v12
	v_lshlrev_b32_e32 v12, 16, v12
	v_and_b32_e32 v83, 0xffff0000, v13
	v_lshlrev_b32_e32 v13, 16, v13
	v_and_b32_e32 v84, 0xffff0000, v14
	v_lshlrev_b32_e32 v14, 16, v14
	v_and_b32_e32 v85, 0xffff0000, v15
	v_lshlrev_b32_e32 v15, 16, v15
	v_and_b32_e32 v86, 0xffff0000, v16
	v_lshlrev_b32_e32 v16, 16, v16
	v_and_b32_e32 v87, 0xffff0000, v17
	v_lshlrev_b32_e32 v17, 16, v17
	v_and_b32_e32 v88, 0xffff0000, v18
	v_lshlrev_b32_e32 v18, 16, v18
	v_and_b32_e32 v89, 0xffff0000, v19
	v_lshlrev_b32_e32 v19, 16, v19
	v_and_b32_e32 v90, 0xffff0000, v20
	v_lshlrev_b32_e32 v20, 16, v20
	v_and_b32_e32 v91, 0xffff0000, v21
	v_lshlrev_b32_e32 v21, 16, v21
	v_and_b32_e32 v92, 0xffff0000, v22
	v_lshlrev_b32_e32 v22, 16, v22
	v_and_b32_e32 v93, 0xffff0000, v23
	v_lshlrev_b32_e32 v23, 16, v23
	v_and_b32_e32 v94, 0xffff0000, v24
	v_lshlrev_b32_e32 v24, 16, v24
	v_and_b32_e32 v95, 0xffff0000, v25
	v_lshlrev_b32_e32 v25, 16, v25
	v_and_b32_e32 v96, 0xffff0000, v26
	v_lshlrev_b32_e32 v26, 16, v26
	v_and_b32_e32 v97, 0xffff0000, v27
	v_lshlrev_b32_e32 v27, 16, v27
	v_and_b32_e32 v98, 0xffff0000, v28
	v_lshlrev_b32_e32 v28, 16, v28
	v_and_b32_e32 v99, 0xffff0000, v29
	v_lshlrev_b32_e32 v29, 16, v29
	v_and_b32_e32 v100, 0xffff0000, v30
	v_lshlrev_b32_e32 v30, 16, v30
	v_add_f32_e32 v4, 0, v12
	v_add_f32_e32 v5, 0, v82
	v_add_f32_e32 v4, v4, v13
	v_add_f32_e32 v5, v5, v83
	v_add_f32_e32 v4, v4, v14
	v_add_f32_e32 v5, v5, v84
	s_cmp_eq_u32 s12, 0
	s_cselect_b32 s32, 0x3f800000, s56
	v_add_f32_e32 v4, v4, v15
	v_add_f32_e32 v5, v5, v85
	v_fma_f32 v6, s32, v4, -v15
	v_fma_f32 v7, s32, v5, -v85
	v_sub_f32_e32 v4, v4, v12
	v_sub_f32_e32 v5, v5, v82
	v_cvt_pk_bf16_f32 v113, v6, v7
	global_store_dword v0, v113, s[28:29]
	s_add_u32 s28, s28, 0x800
	s_addc_u32 s29, s29, 0
	s_cmp_eq_u32 s12, 0
	s_cselect_b32 s32, 0x3f000000, s56
	v_add_f32_e32 v4, v4, v16
	v_add_f32_e32 v5, v5, v86
	v_fma_f32 v6, s32, v4, -v16
	v_fma_f32 v7, s32, v5, -v86
	v_sub_f32_e32 v4, v4, v13
	v_sub_f32_e32 v5, v5, v83
	v_cvt_pk_bf16_f32 v114, v6, v7
	global_store_dword v0, v114, s[28:29]
	s_add_u32 s28, s28, 0x800
	s_addc_u32 s29, s29, 0
	s_cmp_eq_u32 s12, 0
	s_cselect_b32 s32, 0x3eaaaaab, s56
	v_add_f32_e32 v4, v4, v17
	v_add_f32_e32 v5, v5, v87
	v_fma_f32 v6, s32, v4, -v17
	v_fma_f32 v7, s32, v5, -v87
	v_sub_f32_e32 v4, v4, v14
	v_sub_f32_e32 v5, v5, v84
	v_cvt_pk_bf16_f32 v115, v6, v7
	global_store_dword v0, v115, s[28:29]
	s_add_u32 s28, s28, 0x800
	s_addc_u32 s29, s29, 0
	v_add_f32_e32 v4, v4, v18
	v_add_f32_e32 v5, v5, v88
	v_fma_f32 v6, s56, v4, -v18
	v_fma_f32 v7, s56, v5, -v88
	v_sub_f32_e32 v4, v4, v15
	v_sub_f32_e32 v5, v5, v85
	v_cvt_pk_bf16_f32 v116, v6, v7
	global_store_dword v0, v116, s[28:29]
	s_add_u32 s28, s28, 0x800
	s_addc_u32 s29, s29, 0
	v_add_f32_e32 v4, v4, v19
	v_add_f32_e32 v5, v5, v89
	v_fma_f32 v6, s56, v4, -v19
	v_fma_f32 v7, s56, v5, -v89
	v_sub_f32_e32 v4, v4, v16
	v_sub_f32_e32 v5, v5, v86
	v_cvt_pk_bf16_f32 v117, v6, v7
	global_store_dword v0, v117, s[28:29]
	s_add_u32 s28, s28, 0x800
	s_addc_u32 s29, s29, 0
	v_add_f32_e32 v4, v4, v20
	v_add_f32_e32 v5, v5, v90
	v_fma_f32 v6, s56, v4, -v20
	v_fma_f32 v7, s56, v5, -v90
	v_sub_f32_e32 v4, v4, v17
	v_sub_f32_e32 v5, v5, v87
	v_cvt_pk_bf16_f32 v118, v6, v7
	global_store_dword v0, v118, s[28:29]
	s_add_u32 s28, s28, 0x800
	s_addc_u32 s29, s29, 0
	v_add_f32_e32 v4, v4, v21
	v_add_f32_e32 v5, v5, v91
	v_fma_f32 v6, s56, v4, -v21
	v_fma_f32 v7, s56, v5, -v91
	v_sub_f32_e32 v4, v4, v18
	v_sub_f32_e32 v5, v5, v88
	v_cvt_pk_bf16_f32 v119, v6, v7
	global_store_dword v0, v119, s[28:29]
	s_add_u32 s28, s28, 0x800
	s_addc_u32 s29, s29, 0
	v_add_f32_e32 v4, v4, v22
	v_add_f32_e32 v5, v5, v92
	v_fma_f32 v6, s56, v4, -v22
	v_fma_f32 v7, s56, v5, -v92
	v_sub_f32_e32 v4, v4, v19
	v_sub_f32_e32 v5, v5, v89
	v_cvt_pk_bf16_f32 v120, v6, v7
	global_store_dword v0, v120, s[28:29]
	s_add_u32 s28, s28, 0x800
	s_addc_u32 s29, s29, 0
	v_add_f32_e32 v4, v4, v23
	v_add_f32_e32 v5, v5, v93
	v_fma_f32 v6, s56, v4, -v23
	v_fma_f32 v7, s56, v5, -v93
	v_sub_f32_e32 v4, v4, v20
	v_sub_f32_e32 v5, v5, v90
	v_cvt_pk_bf16_f32 v121, v6, v7
	global_store_dword v0, v121, s[28:29]
	s_add_u32 s28, s28, 0x800
	s_addc_u32 s29, s29, 0
	v_add_f32_e32 v4, v4, v24
	v_add_f32_e32 v5, v5, v94
	v_fma_f32 v6, s56, v4, -v24
	v_fma_f32 v7, s56, v5, -v94
	v_sub_f32_e32 v4, v4, v21
	v_sub_f32_e32 v5, v5, v91
	v_cvt_pk_bf16_f32 v122, v6, v7
	global_store_dword v0, v122, s[28:29]
	s_add_u32 s28, s28, 0x800
	s_addc_u32 s29, s29, 0
	v_add_f32_e32 v4, v4, v25
	v_add_f32_e32 v5, v5, v95
	v_fma_f32 v6, s56, v4, -v25
	v_fma_f32 v7, s56, v5, -v95
	v_sub_f32_e32 v4, v4, v22
	v_sub_f32_e32 v5, v5, v92
	v_cvt_pk_bf16_f32 v123, v6, v7
	global_store_dword v0, v123, s[28:29]
	s_add_u32 s28, s28, 0x800
	s_addc_u32 s29, s29, 0
	v_add_f32_e32 v4, v4, v26
	v_add_f32_e32 v5, v5, v96
	v_fma_f32 v6, s56, v4, -v26
	v_fma_f32 v7, s56, v5, -v96
	v_sub_f32_e32 v4, v4, v23
	v_sub_f32_e32 v5, v5, v93
	v_cvt_pk_bf16_f32 v124, v6, v7
	global_store_dword v0, v124, s[28:29]
	s_add_u32 s28, s28, 0x800
	s_addc_u32 s29, s29, 0
	v_add_f32_e32 v4, v4, v27
	v_add_f32_e32 v5, v5, v97
	v_fma_f32 v6, s56, v4, -v27
	v_fma_f32 v7, s56, v5, -v97
	v_sub_f32_e32 v4, v4, v24
	v_sub_f32_e32 v5, v5, v94
	v_cvt_pk_bf16_f32 v125, v6, v7
	global_store_dword v0, v125, s[28:29]
	s_add_u32 s28, s28, 0x800
	s_addc_u32 s29, s29, 0
	v_add_f32_e32 v4, v4, v28
	v_add_f32_e32 v5, v5, v98
	v_fma_f32 v6, s56, v4, -v28
	v_fma_f32 v7, s56, v5, -v98
	v_sub_f32_e32 v4, v4, v25
	v_sub_f32_e32 v5, v5, v95
	v_cvt_pk_bf16_f32 v126, v6, v7
	global_store_dword v0, v126, s[28:29]
	s_add_u32 s28, s28, 0x800
	s_addc_u32 s29, s29, 0
	v_add_f32_e32 v4, v4, v29
	v_add_f32_e32 v5, v5, v99
	v_fma_f32 v6, s56, v4, -v29
	v_fma_f32 v7, s56, v5, -v99
	v_sub_f32_e32 v4, v4, v26
	v_sub_f32_e32 v5, v5, v96
	v_cvt_pk_bf16_f32 v127, v6, v7
	global_store_dword v0, v127, s[28:29]
	s_add_u32 s28, s28, 0x800
	s_addc_u32 s29, s29, 0
	v_add_f32_e32 v4, v4, v30
	v_add_f32_e32 v5, v5, v100
	v_fma_f32 v6, s56, v4, -v30
	v_fma_f32 v7, s56, v5, -v100
	v_sub_f32_e32 v4, v4, v27
	v_sub_f32_e32 v5, v5, v97
	v_cvt_pk_bf16_f32 v128, v6, v7
	global_store_dword v0, v128, s[28:29]
	s_add_u32 s18, s18, 0x1000000
	s_addc_u32 s19, s19, 0
	s_sub_u32 s57, s57, 1
	s_cmp_lg_u32 s57, 0
	s_cbranch_scc1 .Lpool_w4_loop
	s_branch .LBB0_464

; __device__ __forceinline__ float bf2f(bf16_t v) { return __uint_as_float(((unsigned)v) << 16); }
; template <int W> __device__ __forceinline__ void pool_round2(const bf16_t* zpa, bf16_t* mpa, const bf16_t* zpb, bf16_t* mpb, int t0) {
;     float a[W - 1 + 16], c[W - 1 + 16];
; #pragma unroll
;     for (int i = 0; i < W - 1 + 16; ++i) { const int t = t0 - (W - 1) + i; a[i] = (t >= 0) ? bf2f(zpa[(size_t)t * DM]) : 0.f; c[i] = (t >= 0) ? bf2f(zpb[(size_t)t * DM]) : 0.f; }
.Lpool_w2_loop:
	s_sub_u32 s26, s18, 0x800
	s_subb_u32 s27, s19, 0
	global_load_dword v12, v0, s[26:27] nt
	s_add_u32 s26, s26, 0x800
	s_addc_u32 s27, s27, 0
	global_load_dword v13, v0, s[26:27] nt
	s_add_u32 s26, s26, 0x800
	s_addc_u32 s27, s27, 0
	global_load_dword v14, v0, s[26:27] nt
	s_add_u32 s26, s26, 0x800
	s_addc_u32 s27, s27, 0
	global_load_dword v15, v0, s[26:27] nt
	s_add_u32 s26, s26, 0x800
	s_addc_u32 s27, s27, 0
	global_load_dword v16, v0, s[26:27] nt
	s_add_u32 s26, s26, 0x800
	s_addc_u32 s27, s27, 0
	global_load_dword v17, v0, s[26:27] nt
	s_add_u32 s26, s26, 0x800
	s_addc_u32 s27, s27, 0
	global_load_dword v18, v0, s[26:27] nt
	s_add_u32 s26, s26, 0x800
	s_addc_u32 s27, s27, 0
	global_load_dword v19, v0, s[26:27] nt
	s_add_u32 s26, s26, 0x800
	s_addc_u32 s27, s27, 0
	global_load_dword v20, v0, s[26:27] nt
	s_add_u32 s26, s26, 0x800
	s_addc_u32 s27, s27, 0
	global_load_dword v21, v0, s[26:27] nt
	s_add_u32 s26, s26, 0x800
	s_addc_u32 s27, s27, 0
	global_load_dword v22, v0, s[26:27] nt
	s_add_u32 s26, s26, 0x800
	s_addc_u32 s27, s27, 0
	global_load_dword v23, v0, s[26:27] nt
	s_add_u32 s26, s26, 0x800
	s_addc_u32 s27, s27, 0
	global_load_dword v24, v0, s[26:27] nt
	s_add_u32 s26, s26, 0x800
	s_addc_u32 s27, s27, 0
	global_load_dword v25, v0, s[26:27] nt
	s_add_u32 s26, s26, 0x800
	s_addc_u32 s27, s27, 0
	global_load_dword v26, v0, s[26:27] nt
	s_add_u32 s26, s26, 0x800
	s_addc_u32 s27, s27, 0
	global_load_dword v27, v0, s[26:27] nt
	s_add_u32 s26, s26, 0x800
	s_addc_u32 s27, s27, 0
	global_load_dword v28, v0, s[26:27] nt
	s_add_u32 s28, s18, 0x8000000
	s_addc_u32 s29, s19, 0
	s_waitcnt vmcnt(0)
; __device__ __forceinline__ bf16_t f2bf(float f) { unsigned u = __float_as_uint(f); u += 0x7FFFu + ((u >> 16) & 1u); return (bf16_t)(u >> 16); }
; template <int W> __device__ __forceinline__ void pool_round2(const bf16_t* zpa, bf16_t* mpa, const bf16_t* zpb, bf16_t* mpb, int t0) {
;     ...
;     float sa = 0.f, sc = 0.f;
; #pragma unroll
;     for (int i = 0; i < W - 1; ++i) { sa += a[i]; sc += c[i]; }
; #pragma unroll
;     for (int j = 0; j < 16; ++j) {
;         const int t = t0 + j; const float va = a[W - 1 + j], vc = c[W - 1 + j]; sa += va; sc += vc;
;         const float inv = 1.0f / (float)((t + 1 < W) ? t + 1 : W);
;         mpa[(size_t)t * DM] = f2bf(sa * inv - va); mpb[(size_t)t * DM] = f2bf(sc * inv - vc);
;         sa -= a[j]; sc -= c[j];
;     }
	v_and_b32_e32 v12, s14, v12
	v_and_b32_e32 v82, 0xffff0000, v12
	v_lshlrev_b32_e32 v12, 16, v12
	v_and_b32_e32 v83, 0xffff0000, v13
	v_lshlrev_b32_e32 v13, 16, v13
	v_and_b32_e32 v84, 0xffff0000, v14
	v_lshlrev_b32_e32 v14, 16, v14
	v_and_b32_e32 v85, 0xffff0000, v15
	v_lshlrev_b32_e32 v15, 16, v15
	v_and_b32_e32 v86, 0xffff0000, v16
	v_lshlrev_b32_e32 v16, 16, v16
	v_and_b32_e32 v87, 0xffff0000, v17
	v_lshlrev_b32_e32 v17, 16, v17
	v_and_b32_e32 v88, 0xffff0000, v18
	v_lshlrev_b32_e32 v18, 16, v18
	v_and_b32_e32 v89, 0xffff0000, v19
	v_lshlrev_b32_e32 v19, 16, v19
	v_and_b32_e32 v90, 0xffff0000, v20
	v_lshlrev_b32_e32 v20, 16, v20
	v_and_b32_e32 v91, 0xffff0000, v21
	v_lshlrev_b32_e32 v21, 16, v21
	v_and_b32_e32 v92, 0xffff0000, v22
	v_lshlrev_b32_e32 v22, 16, v22
	v_and_b32_e32 v93, 0xffff0000, v23
	v_lshlrev_b32_e32 v23, 16, v23
	v_and_b32_e32 v94, 0xffff0000, v24
	v_lshlrev_b32_e32 v24, 16, v24
	v_and_b32_e32 v95, 0xffff0000, v25
	v_lshlrev_b32_e32 v25, 16, v25
	v_and_b32_e32 v96, 0xffff0000, v26
	v_lshlrev_b32_e32 v26, 16, v26
	v_and_b32_e32 v97, 0xffff0000, v27
	v_lshlrev_b32_e32 v27, 16, v27
	v_and_b32_e32 v98, 0xffff0000, v28
	v_lshlrev_b32_e32 v28, 16, v28
	v_add_f32_e32 v4, 0, v12
	v_add_f32_e32 v5, 0, v82
	s_cmp_eq_u32 s12, 0
	s_cselect_b32 s32, 0x3f800000, s56
	v_add_f32_e32 v4, v4, v13
	v_add_f32_e32 v5, v5, v83
	v_fma_f32 v6, s32, v4, -v13
	v_fma_f32 v7, s32, v5, -v83
	v_sub_f32_e32 v4, v4, v12
	v_sub_f32_e32 v5, v5, v82
	v_cvt_pk_bf16_f32 v113, v6, v7
	global_store_dword v0, v113, s[28:29]
	s_add_u32 s28, s28, 0x800
	s_addc_u32 s29, s29, 0
	v_add_f32_e32 v4, v4, v14
	v_add_f32_e32 v5, v5, v84
	v_fma_f32 v6, s56, v4, -v14
	v_fma_f32 v7, s56, v5, -v84
	v_sub_f32_e32 v4, v4, v13
	v_sub_f32_e32 v5, v5, v83
	v_cvt_pk_bf16_f32 v114, v6, v7
	global_store_dword v0, v114, s[28:29]
	s_add_u32 s28, s28, 0x800
	s_addc_u32 s29, s29, 0
	v_add_f32_e32 v4, v4, v15
	v_add_f32_e32 v5, v5, v85
	v_fma_f32 v6, s56, v4, -v15
	v_fma_f32 v7, s56, v5, -v85
	v_sub_f32_e32 v4, v4, v14
	v_sub_f32_e32 v5, v5, v84
	v_cvt_pk_bf16_f32 v115, v6, v7
	global_store_dword v0, v115, s[28:29]
	s_add_u32 s28, s28, 0x800
	s_addc_u32 s29, s29, 0
	v_add_f32_e32 v4, v4, v16
	v_add_f32_e32 v5, v5, v86
	v_fma_f32 v6, s56, v4, -v16
	v_fma_f32 v7, s56, v5, -v86
	v_sub_f32_e32 v4, v4, v15
	v_sub_f32_e32 v5, v5, v85
	v_cvt_pk_bf16_f32 v116, v6, v7
	global_store_dword v0, v116, s[28:29]
	s_add_u32 s28, s28, 0x800
	s_addc_u32 s29, s29, 0
	v_add_f32_e32 v4, v4, v17
	v_add_f32_e32 v5, v5, v87
	v_fma_f32 v6, s56, v4, -v17
	v_fma_f32 v7, s56, v5, -v87
	v_sub_f32_e32 v4, v4, v16
	v_sub_f32_e32 v5, v5, v86
	v_cvt_pk_bf16_f32 v117, v6, v7
	global_store_dword v0, v117, s[28:29]
	s_add_u32 s28, s28, 0x800
	s_addc_u32 s29, s29, 0
	v_add_f32_e32 v4, v4, v18
	v_add_f32_e32 v5, v5, v88
	v_fma_f32 v6, s56, v4, -v18
	v_fma_f32 v7, s56, v5, -v88
	v_sub_f32_e32 v4, v4, v17
	v_sub_f32_e32 v5, v5, v87
	v_cvt_pk_bf16_f32 v118, v6, v7
	global_store_dword v0, v118, s[28:29]
	s_add_u32 s28, s28, 0x800
	s_addc_u32 s29, s29, 0
	v_add_f32_e32 v4, v4, v19
	v_add_f32_e32 v5, v5, v89
	v_fma_f32 v6, s56, v4, -v19
	v_fma_f32 v7, s56, v5, -v89
	v_sub_f32_e32 v4, v4, v18
	v_sub_f32_e32 v5, v5, v88
	v_cvt_pk_bf16_f32 v119, v6, v7
	global_store_dword v0, v119, s[28:29]
	s_add_u32 s28, s28, 0x800
	s_addc_u32 s29, s29, 0
	v_add_f32_e32 v4, v4, v20
	v_add_f32_e32 v5, v5, v90
	v_fma_f32 v6, s56, v4, -v20
	v_fma_f32 v7, s56, v5, -v90
	v_sub_f32_e32 v4, v4, v19
	v_sub_f32_e32 v5, v5, v89
	v_cvt_pk_bf16_f32 v120, v6, v7
	global_store_dword v0, v120, s[28:29]
	s_add_u32 s28, s28, 0x800
	s_addc_u32 s29, s29, 0
	v_add_f32_e32 v4, v4, v21
	v_add_f32_e32 v5, v5, v91
	v_fma_f32 v6, s56, v4, -v21
	v_fma_f32 v7, s56, v5, -v91
	v_sub_f32_e32 v4, v4, v20
	v_sub_f32_e32 v5, v5, v90
	v_cvt_pk_bf16_f32 v121, v6, v7
	global_store_dword v0, v121, s[28:29]
	s_add_u32 s28, s28, 0x800
	s_addc_u32 s29, s29, 0
	v_add_f32_e32 v4, v4, v22
	v_add_f32_e32 v5, v5, v92
	v_fma_f32 v6, s56, v4, -v22
	v_fma_f32 v7, s56, v5, -v92
	v_sub_f32_e32 v4, v4, v21
	v_sub_f32_e32 v5, v5, v91
	v_cvt_pk_bf16_f32 v122, v6, v7
	global_store_dword v0, v122, s[28:29]
	s_add_u32 s28, s28, 0x800
	s_addc_u32 s29, s29, 0
	v_add_f32_e32 v4, v4, v23
	v_add_f32_e32 v5, v5, v93
	v_fma_f32 v6, s56, v4, -v23
	v_fma_f32 v7, s56, v5, -v93
	v_sub_f32_e32 v4, v4, v22
	v_sub_f32_e32 v5, v5, v92
	v_cvt_pk_bf16_f32 v123, v6, v7
	global_store_dword v0, v123, s[28:29]
	s_add_u32 s28, s28, 0x800
	s_addc_u32 s29, s29, 0
	v_add_f32_e32 v4, v4, v24
	v_add_f32_e32 v5, v5, v94
	v_fma_f32 v6, s56, v4, -v24
	v_fma_f32 v7, s56, v5, -v94
	v_sub_f32_e32 v4, v4, v23
	v_sub_f32_e32 v5, v5, v93
	v_cvt_pk_bf16_f32 v124, v6, v7
	global_store_dword v0, v124, s[28:29]
	s_add_u32 s28, s28, 0x800
	s_addc_u32 s29, s29, 0
	v_add_f32_e32 v4, v4, v25
	v_add_f32_e32 v5, v5, v95
	v_fma_f32 v6, s56, v4, -v25
	v_fma_f32 v7, s56, v5, -v95
	v_sub_f32_e32 v4, v4, v24
	v_sub_f32_e32 v5, v5, v94
	v_cvt_pk_bf16_f32 v125, v6, v7
	global_store_dword v0, v125, s[28:29]
	s_add_u32 s28, s28, 0x800
	s_addc_u32 s29, s29, 0
	v_add_f32_e32 v4, v4, v26
	v_add_f32_e32 v5, v5, v96
	v_fma_f32 v6, s56, v4, -v26
	v_fma_f32 v7, s56, v5, -v96
	v_sub_f32_e32 v4, v4, v25
	v_sub_f32_e32 v5, v5, v95
	v_cvt_pk_bf16_f32 v126, v6, v7
	global_store_dword v0, v126, s[28:29]
	s_add_u32 s28, s28, 0x800
	s_addc_u32 s29, s29, 0
	v_add_f32_e32 v4, v4, v27
	v_add_f32_e32 v5, v5, v97
	v_fma_f32 v6, s56, v4, -v27
	v_fma_f32 v7, s56, v5, -v97
	v_sub_f32_e32 v4, v4, v26
	v_sub_f32_e32 v5, v5, v96
	v_cvt_pk_bf16_f32 v127, v6, v7
	global_store_dword v0, v127, s[28:29]
	s_add_u32 s28, s28, 0x800
	s_addc_u32 s29, s29, 0
	v_add_f32_e32 v4, v4, v28
	v_add_f32_e32 v5, v5, v98
	v_fma_f32 v6, s56, v4, -v28
	v_fma_f32 v7, s56, v5, -v98
	v_sub_f32_e32 v4, v4, v27
	v_sub_f32_e32 v5, v5, v97
	v_cvt_pk_bf16_f32 v128, v6, v7
	global_store_dword v0, v128, s[28:29]
	s_add_u32 s18, s18, 0x1000000
	s_addc_u32 s19, s19, 0
	s_sub_u32 s57, s57, 1
	s_cmp_lg_u32 s57, 0
	s_cbranch_scc1 .Lpool_w2_loop
